# K-loop LDS-DMA loads use SGPR base + 32-bit VGPR offset (no 64-bit VALU address math); B-fragment ds_reads from one base VGPR with immediate offsets
# speedup vs baseline: 1.0238x; 1.0072x over previous
.LBB0_99:
	s_add_u32 s16, s14, 0xfffc0080
	s_addc_u32 s17, s15, -1
	s_add_i32 s45, 0, 0x10000
	v_add_u32_e32 v249, s45, v139
	ds_read_b128 v[142:145], v249
	ds_read_b128 v[146:149], v249 offset:1024
	ds_read_b128 v[150:153], v249 offset:2048
	ds_read_b128 v[154:157], v249 offset:3072
	s_cmp_eq_u32 s44, 12
	s_cselect_b32 s19, s9, s17
	s_cselect_b32 s18, s40, s16
	s_cselect_b32 s17, s7, s43
	s_cselect_b32 s16, s41, s42
	s_add_i32 s48, 0, 0x14000
	ds_read_b128 v[204:207], v249 offset:16384
	ds_read_b128 v[208:211], v249 offset:17408
	ds_read_b128 v[212:215], v249 offset:18432
	ds_read_b128 v[216:219], v249 offset:19456
	s_add_i32 m0, s26, 0xc000
	ds_read_b128 v[158:161], v140
	ds_read_b128 v[162:165], v140 offset:1024
	ds_read_b128 v[166:169], v140 offset:2048
	ds_read_b128 v[170:173], v140 offset:3072
	ds_read_b128 v[174:177], v140 offset:4096
	ds_read_b128 v[178:181], v140 offset:5120
	ds_read_b128 v[182:185], v140 offset:6144
	ds_read_b128 v[186:189], v140 offset:7168
	global_load_lds_dwordx4 v134, s[14:15]
	s_add_i32 m0, s26, 0xe000
	s_nop 0
	global_load_lds_dwordx4 v136, s[14:15]
	s_waitcnt vmcnt(8) lgkmcnt(0)
	s_barrier
	s_setprio 1
	v_mfma_f32_16x16x32_bf16 v[126:129], v[142:145], v[158:161], v[126:129]
	v_mfma_f32_16x16x32_bf16 v[122:125], v[150:153], v[158:161], v[122:125]
	v_mfma_f32_16x16x32_bf16 v[110:113], v[142:145], v[166:169], v[110:113]
	v_mfma_f32_16x16x32_bf16 v[106:109], v[150:153], v[166:169], v[106:109]
	v_mfma_f32_16x16x32_bf16 v[94:97], v[142:145], v[174:177], v[94:97]
	v_mfma_f32_16x16x32_bf16 v[90:93], v[150:153], v[174:177], v[90:93]
	v_mfma_f32_16x16x32_bf16 v[78:81], v[142:145], v[182:185], v[78:81]
	v_mfma_f32_16x16x32_bf16 v[74:77], v[150:153], v[182:185], v[74:77]
	v_mfma_f32_16x16x32_bf16 v[126:129], v[146:149], v[162:165], v[126:129]
	v_mfma_f32_16x16x32_bf16 v[122:125], v[154:157], v[162:165], v[122:125]
	v_mfma_f32_16x16x32_bf16 v[110:113], v[146:149], v[170:173], v[110:113]
	v_mfma_f32_16x16x32_bf16 v[106:109], v[154:157], v[170:173], v[106:109]
	v_mfma_f32_16x16x32_bf16 v[94:97], v[146:149], v[178:181], v[94:97]
	v_mfma_f32_16x16x32_bf16 v[90:93], v[154:157], v[178:181], v[90:93]
	v_mfma_f32_16x16x32_bf16 v[78:81], v[146:149], v[186:189], v[78:81]
	v_mfma_f32_16x16x32_bf16 v[74:77], v[154:157], v[186:189], v[74:77]
	v_mfma_f32_16x16x32_bf16 v[118:121], v[204:207], v[158:161], v[118:121]
	v_mfma_f32_16x16x32_bf16 v[114:117], v[212:215], v[158:161], v[114:117]
	v_mfma_f32_16x16x32_bf16 v[102:105], v[204:207], v[166:169], v[102:105]
	v_mfma_f32_16x16x32_bf16 v[98:101], v[212:215], v[166:169], v[98:101]
	v_mfma_f32_16x16x32_bf16 v[86:89], v[204:207], v[174:177], v[86:89]
	v_mfma_f32_16x16x32_bf16 v[82:85], v[212:215], v[174:177], v[82:85]
	v_mfma_f32_16x16x32_bf16 v[70:73], v[204:207], v[182:185], v[70:73]
	v_mfma_f32_16x16x32_bf16 v[66:69], v[212:215], v[182:185], v[66:69]
	v_mfma_f32_16x16x32_bf16 v[118:121], v[208:211], v[162:165], v[118:121]
	v_mfma_f32_16x16x32_bf16 v[114:117], v[216:219], v[162:165], v[114:117]
	v_mfma_f32_16x16x32_bf16 v[102:105], v[208:211], v[170:173], v[102:105]
	v_mfma_f32_16x16x32_bf16 v[98:101], v[216:219], v[170:173], v[98:101]
	v_mfma_f32_16x16x32_bf16 v[86:89], v[208:211], v[178:181], v[86:89]
	v_mfma_f32_16x16x32_bf16 v[82:85], v[216:219], v[178:181], v[82:85]
	v_mfma_f32_16x16x32_bf16 v[70:73], v[208:211], v[186:189], v[70:73]
	v_mfma_f32_16x16x32_bf16 v[66:69], v[216:219], v[186:189], v[66:69]
	s_setprio 0
	s_barrier
	ds_read_b128 v[158:161], v140 offset:16384
	ds_read_b128 v[162:165], v140 offset:17408
	ds_read_b128 v[166:169], v140 offset:18432
	ds_read_b128 v[170:173], v140 offset:19456
	ds_read_b128 v[174:177], v140 offset:20480
	ds_read_b128 v[178:181], v140 offset:21504
	ds_read_b128 v[182:185], v140 offset:22528
	ds_read_b128 v[186:189], v140 offset:23552
	s_add_i32 s45, s45, s25
	s_mov_b32 m0, s45
	s_nop 0
	global_load_lds_dwordx4 v132, s[16:17]
	s_add_i32 m0, s45, 0x2000
	s_nop 0
	global_load_lds_dwordx4 v130, s[16:17]
	s_mov_b32 m0, s26
	s_add_u32 s98, s18, 0x80
	s_addc_u32 s99, s19, 0
	global_load_lds_dwordx4 v132, s[18:19]
	s_mov_b32 m0, s27
	s_nop 0
	global_load_lds_dwordx4 v130, s[18:19]
	s_add_u32 s46, s16, 0x40000
	s_addc_u32 s47, s17, 0
	s_add_i32 s45, s48, s25
	s_mov_b32 m0, s45
	s_nop 0
	global_load_lds_dwordx4 v132, s[46:47]
	s_add_i32 m0, s45, 0x2000
	s_nop 0
	global_load_lds_dwordx4 v130, s[46:47]
	s_waitcnt vmcnt(8) lgkmcnt(0)
	s_barrier
	s_setprio 1
	v_mfma_f32_16x16x32_bf16 v[62:65], v[142:145], v[158:161], v[62:65]
	v_mfma_f32_16x16x32_bf16 v[58:61], v[150:153], v[158:161], v[58:61]
	v_mfma_f32_16x16x32_bf16 v[46:49], v[142:145], v[166:169], v[46:49]
	v_mfma_f32_16x16x32_bf16 v[42:45], v[150:153], v[166:169], v[42:45]
	v_mfma_f32_16x16x32_bf16 v[30:33], v[142:145], v[174:177], v[30:33]
	v_mfma_f32_16x16x32_bf16 v[26:29], v[150:153], v[174:177], v[26:29]
	v_mfma_f32_16x16x32_bf16 v[14:17], v[142:145], v[182:185], v[14:17]
	v_mfma_f32_16x16x32_bf16 v[10:13], v[150:153], v[182:185], v[10:13]
	v_mfma_f32_16x16x32_bf16 v[62:65], v[146:149], v[162:165], v[62:65]
	v_mfma_f32_16x16x32_bf16 v[58:61], v[154:157], v[162:165], v[58:61]
	v_mfma_f32_16x16x32_bf16 v[46:49], v[146:149], v[170:173], v[46:49]
	v_mfma_f32_16x16x32_bf16 v[42:45], v[154:157], v[170:173], v[42:45]
	v_mfma_f32_16x16x32_bf16 v[30:33], v[146:149], v[178:181], v[30:33]
	v_mfma_f32_16x16x32_bf16 v[26:29], v[154:157], v[178:181], v[26:29]
	v_mfma_f32_16x16x32_bf16 v[14:17], v[146:149], v[186:189], v[14:17]
	v_mfma_f32_16x16x32_bf16 v[10:13], v[154:157], v[186:189], v[10:13]
	v_mfma_f32_16x16x32_bf16 v[54:57], v[204:207], v[158:161], v[54:57]
	v_mfma_f32_16x16x32_bf16 v[50:53], v[212:215], v[158:161], v[50:53]
	v_mfma_f32_16x16x32_bf16 v[38:41], v[204:207], v[166:169], v[38:41]
	v_mfma_f32_16x16x32_bf16 v[34:37], v[212:215], v[166:169], v[34:37]
	v_mfma_f32_16x16x32_bf16 v[22:25], v[204:207], v[174:177], v[22:25]
	v_mfma_f32_16x16x32_bf16 v[18:21], v[212:215], v[174:177], v[18:21]
	v_mfma_f32_16x16x32_bf16 v[6:9], v[204:207], v[182:185], v[6:9]
	v_mfma_f32_16x16x32_bf16 v[2:5], v[212:215], v[182:185], v[2:5]
	v_mfma_f32_16x16x32_bf16 v[54:57], v[208:211], v[162:165], v[54:57]
	v_mfma_f32_16x16x32_bf16 v[50:53], v[216:219], v[162:165], v[50:53]
	v_mfma_f32_16x16x32_bf16 v[38:41], v[208:211], v[170:173], v[38:41]
	v_mfma_f32_16x16x32_bf16 v[34:37], v[216:219], v[170:173], v[34:37]
	v_mfma_f32_16x16x32_bf16 v[22:25], v[208:211], v[178:181], v[22:25]
	v_mfma_f32_16x16x32_bf16 v[18:21], v[216:219], v[178:181], v[18:21]
	v_mfma_f32_16x16x32_bf16 v[6:9], v[208:211], v[186:189], v[6:9]
	v_mfma_f32_16x16x32_bf16 v[2:5], v[216:219], v[186:189], v[2:5]
	s_setprio 0
	s_barrier
	s_add_i32 s45, 0, 0x18000
	ds_read_b128 v[142:145], v249 offset:32768
	ds_read_b128 v[146:149], v249 offset:33792
	ds_read_b128 v[150:153], v249 offset:34816
	ds_read_b128 v[154:157], v249 offset:35840
	s_add_u32 s18, s18, 0x40000
	s_addc_u32 s19, s19, 0
	s_mov_b32 m0, s28
	ds_read_b128 v[158:161], v140 offset:32768
	ds_read_b128 v[162:165], v140 offset:33792
	ds_read_b128 v[166:169], v140 offset:34816
	ds_read_b128 v[170:173], v140 offset:35840
	ds_read_b128 v[174:177], v140 offset:36864
	ds_read_b128 v[178:181], v140 offset:37888
	ds_read_b128 v[182:185], v140 offset:38912
	ds_read_b128 v[186:189], v140 offset:39936
	global_load_lds_dwordx4 v132, s[18:19]
	s_mov_b32 m0, s29
	s_nop 0
	global_load_lds_dwordx4 v130, s[18:19]
	s_add_i32 s18, 0, 0x1c000
	ds_read_b128 v[204:207], v249 offset:49152
	ds_read_b128 v[208:211], v249 offset:50176
	ds_read_b128 v[212:215], v249 offset:51200
	ds_read_b128 v[216:219], v249 offset:52224
	s_waitcnt vmcnt(8) lgkmcnt(0)
	s_barrier
	s_setprio 1
	v_mfma_f32_16x16x32_bf16 v[126:129], v[142:145], v[158:161], v[126:129]
	v_mfma_f32_16x16x32_bf16 v[122:125], v[150:153], v[158:161], v[122:125]
	v_mfma_f32_16x16x32_bf16 v[110:113], v[142:145], v[166:169], v[110:113]
	v_mfma_f32_16x16x32_bf16 v[106:109], v[150:153], v[166:169], v[106:109]
	v_mfma_f32_16x16x32_bf16 v[94:97], v[142:145], v[174:177], v[94:97]
	v_mfma_f32_16x16x32_bf16 v[90:93], v[150:153], v[174:177], v[90:93]
	v_mfma_f32_16x16x32_bf16 v[78:81], v[142:145], v[182:185], v[78:81]
	v_mfma_f32_16x16x32_bf16 v[74:77], v[150:153], v[182:185], v[74:77]
	v_mfma_f32_16x16x32_bf16 v[126:129], v[146:149], v[162:165], v[126:129]
	v_mfma_f32_16x16x32_bf16 v[122:125], v[154:157], v[162:165], v[122:125]
	v_mfma_f32_16x16x32_bf16 v[110:113], v[146:149], v[170:173], v[110:113]
	v_mfma_f32_16x16x32_bf16 v[106:109], v[154:157], v[170:173], v[106:109]
	v_mfma_f32_16x16x32_bf16 v[94:97], v[146:149], v[178:181], v[94:97]
	v_mfma_f32_16x16x32_bf16 v[90:93], v[154:157], v[178:181], v[90:93]
	v_mfma_f32_16x16x32_bf16 v[78:81], v[146:149], v[186:189], v[78:81]
	v_mfma_f32_16x16x32_bf16 v[74:77], v[154:157], v[186:189], v[74:77]
	v_mfma_f32_16x16x32_bf16 v[118:121], v[204:207], v[158:161], v[118:121]
	v_mfma_f32_16x16x32_bf16 v[114:117], v[212:215], v[158:161], v[114:117]
	v_mfma_f32_16x16x32_bf16 v[102:105], v[204:207], v[166:169], v[102:105]
	v_mfma_f32_16x16x32_bf16 v[98:101], v[212:215], v[166:169], v[98:101]
	v_mfma_f32_16x16x32_bf16 v[86:89], v[204:207], v[174:177], v[86:89]
	v_mfma_f32_16x16x32_bf16 v[82:85], v[212:215], v[174:177], v[82:85]
	v_mfma_f32_16x16x32_bf16 v[70:73], v[204:207], v[182:185], v[70:73]
	v_mfma_f32_16x16x32_bf16 v[66:69], v[212:215], v[182:185], v[66:69]
	v_mfma_f32_16x16x32_bf16 v[118:121], v[208:211], v[162:165], v[118:121]
	v_mfma_f32_16x16x32_bf16 v[114:117], v[216:219], v[162:165], v[114:117]
	v_mfma_f32_16x16x32_bf16 v[102:105], v[208:211], v[170:173], v[102:105]
	v_mfma_f32_16x16x32_bf16 v[98:101], v[216:219], v[170:173], v[98:101]
	v_mfma_f32_16x16x32_bf16 v[86:89], v[208:211], v[178:181], v[86:89]
	v_mfma_f32_16x16x32_bf16 v[82:85], v[216:219], v[178:181], v[82:85]
	v_mfma_f32_16x16x32_bf16 v[70:73], v[208:211], v[186:189], v[70:73]
	v_mfma_f32_16x16x32_bf16 v[66:69], v[216:219], v[186:189], v[66:69]
	s_setprio 0
	s_barrier
	ds_read_b128 v[158:161], v140 offset:49152
	ds_read_b128 v[162:165], v140 offset:50176
	ds_read_b128 v[166:169], v140 offset:51200
	ds_read_b128 v[170:173], v140 offset:52224
	ds_read_b128 v[174:177], v140 offset:53248
	ds_read_b128 v[178:181], v140 offset:54272
	ds_read_b128 v[182:185], v140 offset:55296
	ds_read_b128 v[186:189], v140 offset:56320
	s_add_i32 s19, s45, s25
	s_mov_b32 m0, s19
	s_add_u32 vcc_lo, s16, 0x80
	s_addc_u32 vcc_hi, s17, 0
	global_load_lds_dwordx4 v132, vcc
	s_add_i32 m0, s19, 0x2000
	s_nop 0
	global_load_lds_dwordx4 v130, vcc
	s_mov_b32 m0, s30
	s_nop 0
	global_load_lds_dwordx4 v132, s[98:99]
	s_mov_b32 m0, s31
	s_nop 0
	global_load_lds_dwordx4 v130, s[98:99]
	s_add_u32 s16, s16, 0x40080
	s_addc_u32 s17, s17, 0
	s_add_i32 s18, s18, s25
	s_mov_b32 m0, s18
	s_nop 0
	global_load_lds_dwordx4 v132, s[16:17]
	s_add_i32 m0, s18, 0x2000
	s_nop 0
	global_load_lds_dwordx4 v130, s[16:17]
	s_waitcnt vmcnt(8) lgkmcnt(0)
	s_barrier
	s_setprio 1
	v_mfma_f32_16x16x32_bf16 v[62:65], v[142:145], v[158:161], v[62:65]
	v_mfma_f32_16x16x32_bf16 v[58:61], v[150:153], v[158:161], v[58:61]
	v_mfma_f32_16x16x32_bf16 v[46:49], v[142:145], v[166:169], v[46:49]
	v_mfma_f32_16x16x32_bf16 v[42:45], v[150:153], v[166:169], v[42:45]
	v_mfma_f32_16x16x32_bf16 v[30:33], v[142:145], v[174:177], v[30:33]
	v_mfma_f32_16x16x32_bf16 v[26:29], v[150:153], v[174:177], v[26:29]
	v_mfma_f32_16x16x32_bf16 v[14:17], v[142:145], v[182:185], v[14:17]
	v_mfma_f32_16x16x32_bf16 v[10:13], v[150:153], v[182:185], v[10:13]
	v_mfma_f32_16x16x32_bf16 v[62:65], v[146:149], v[162:165], v[62:65]
	v_mfma_f32_16x16x32_bf16 v[58:61], v[154:157], v[162:165], v[58:61]
	v_mfma_f32_16x16x32_bf16 v[46:49], v[146:149], v[170:173], v[46:49]
	v_mfma_f32_16x16x32_bf16 v[42:45], v[154:157], v[170:173], v[42:45]
	v_mfma_f32_16x16x32_bf16 v[30:33], v[146:149], v[178:181], v[30:33]
	v_mfma_f32_16x16x32_bf16 v[26:29], v[154:157], v[178:181], v[26:29]
	v_mfma_f32_16x16x32_bf16 v[14:17], v[146:149], v[186:189], v[14:17]
	v_mfma_f32_16x16x32_bf16 v[10:13], v[154:157], v[186:189], v[10:13]
	v_mfma_f32_16x16x32_bf16 v[54:57], v[204:207], v[158:161], v[54:57]
	v_mfma_f32_16x16x32_bf16 v[50:53], v[212:215], v[158:161], v[50:53]
	v_mfma_f32_16x16x32_bf16 v[38:41], v[204:207], v[166:169], v[38:41]
	v_mfma_f32_16x16x32_bf16 v[34:37], v[212:215], v[166:169], v[34:37]
	v_mfma_f32_16x16x32_bf16 v[22:25], v[204:207], v[174:177], v[22:25]
	v_mfma_f32_16x16x32_bf16 v[18:21], v[212:215], v[174:177], v[18:21]
	v_mfma_f32_16x16x32_bf16 v[6:9], v[204:207], v[182:185], v[6:9]
	v_mfma_f32_16x16x32_bf16 v[2:5], v[212:215], v[182:185], v[2:5]
	v_mfma_f32_16x16x32_bf16 v[54:57], v[208:211], v[162:165], v[54:57]
	v_mfma_f32_16x16x32_bf16 v[50:53], v[216:219], v[162:165], v[50:53]
	v_mfma_f32_16x16x32_bf16 v[38:41], v[208:211], v[170:173], v[38:41]
	v_mfma_f32_16x16x32_bf16 v[34:37], v[216:219], v[170:173], v[34:37]
	v_mfma_f32_16x16x32_bf16 v[22:25], v[208:211], v[178:181], v[22:25]
	v_mfma_f32_16x16x32_bf16 v[18:21], v[216:219], v[178:181], v[18:21]
	v_mfma_f32_16x16x32_bf16 v[6:9], v[208:211], v[186:189], v[6:9]
	v_mfma_f32_16x16x32_bf16 v[2:5], v[216:219], v[186:189], v[2:5]
	s_setprio 0
	s_add_i32 s44, s44, 2
	s_add_u32 s14, s14, 0x100
	s_addc_u32 s15, s15, 0
	s_add_u32 s42, s42, 0x100
	s_addc_u32 s43, s43, 0
	s_cmp_gt_u32 s44, 13
	s_barrier
	s_cbranch_scc0 .LBB0_99
	v_lshl_add_u32 v141, s37, 8, v138
	v_lshl_add_u32 v141, v141, 2, 0
	v_add_u32_e32 v142, 0x20040, v141
	ds_read2_b32 v[144:145], v142 offset1:16
	v_pk_mul_f32 v[124:125], v[128:129], v[124:125]
	v_pk_mul_f32 v[122:123], v[126:127], v[122:123]
	v_pk_mul_f32 v[114:115], v[118:119], v[114:115]
	v_pk_mul_f32 v[116:117], v[120:121], v[116:117]
	s_waitcnt lgkmcnt(0)
	v_mul_f32_e32 v146, 0xbfb8aa3b, v144
	v_pk_mul_f32 v[148:149], v[126:127], v[146:147] op_sel_hi:[1,0]
	v_pk_mul_f32 v[126:127], v[128:129], v[146:147] op_sel_hi:[1,0]
	v_pk_mul_f32 v[128:129], v[118:119], v[146:147] op_sel_hi:[1,0]
	v_pk_mul_f32 v[118:119], v[120:121], v[146:147] op_sel_hi:[1,0]
	v_exp_f32_e32 v128, v128
	v_exp_f32_e32 v129, v129
	v_exp_f32_e32 v148, v148
	v_exp_f32_e32 v149, v149
	v_exp_f32_e32 v126, v126
	v_exp_f32_e32 v127, v127
	v_exp_f32_e32 v118, v118
	v_exp_f32_e32 v119, v119
	v_pk_add_f32 v[128:129], v[128:129], 1.0 op_sel_hi:[1,0]
	v_pk_add_f32 v[120:121], v[148:149], 1.0 op_sel_hi:[1,0]
	v_pk_add_f32 v[126:127], v[126:127], 1.0 op_sel_hi:[1,0]
	v_rcp_f32_e32 v128, v128
	v_rcp_f32_e32 v129, v129
	v_pk_add_f32 v[118:119], v[118:119], 1.0 op_sel_hi:[1,0]
	v_rcp_f32_e32 v120, v120
	v_rcp_f32_e32 v121, v121
	v_rcp_f32_e32 v126, v126
	v_rcp_f32_e32 v127, v127
	v_rcp_f32_e32 v118, v118
	v_rcp_f32_e32 v119, v119
	v_mul_f32_e32 v144, v144, v144
	v_pk_mul_f32 v[114:115], v[114:115], v[144:145] op_sel_hi:[1,0]
	s_lshl_b32 s14, s35, 7
	v_pk_mul_f32 v[122:123], v[122:123], v[144:145] op_sel_hi:[1,0]
	v_pk_mul_f32 v[124:125], v[124:125], v[144:145] op_sel_hi:[1,0]
	v_pk_mul_f32 v[116:117], v[116:117], v[144:145] op_sel_hi:[1,0]
	v_pk_mul_f32 v[114:115], v[114:115], v[128:129]
	v_lshl_add_u32 v141, s36, 8, v138
	s_ashr_i32 s15, s14, 31
	v_pk_mul_f32 v[120:121], v[122:123], v[120:121]
	v_pk_mul_f32 v[122:123], v[124:125], v[126:127]
	v_pk_mul_f32 v[124:125], v[116:117], v[118:119]
	v_cvt_pk_bf16_f32 v118, v114, v115
	v_mov_b64_e32 v[114:115], s[0:1]
	s_movk_i32 s7, 0x1600
	v_cvt_pk_bf16_f32 v116, v120, v121
	v_mad_i64_i32 v[120:121], s[16:17], v141, s7, v[114:115]
	s_lshl_b64 s[14:15], s[14:15], 1
	v_lshl_add_u64 v[120:121], v[120:121], 0, s[14:15]
	v_lshl_add_u64 v[120:121], v[120:121], 0, s[96:97]
	v_lshl_add_u64 v[120:121], v[120:121], 0, v[190:191]
	v_cvt_pk_bf16_f32 v117, v122, v123
	v_cvt_pk_bf16_f32 v119, v124, v125
	global_store_dwordx4 v[120:121], v[116:119], off
	v_pk_mul_f32 v[108:109], v[112:113], v[108:109]
	v_pk_mul_f32 v[106:107], v[110:111], v[106:107]
	v_mul_f32_e32 v116, 0xbfb8aa3b, v145
	v_pk_mul_f32 v[120:121], v[110:111], v[116:117] op_sel_hi:[1,0]
	v_pk_mul_f32 v[110:111], v[112:113], v[116:117] op_sel_hi:[1,0]
	v_exp_f32_e32 v120, v120
	v_exp_f32_e32 v121, v121
	v_pk_mul_f32 v[112:113], v[102:103], v[116:117] op_sel_hi:[1,0]
	v_pk_mul_f32 v[98:99], v[102:103], v[98:99]
	v_pk_mul_f32 v[102:103], v[104:105], v[116:117] op_sel_hi:[1,0]
	v_exp_f32_e32 v110, v110
	v_exp_f32_e32 v111, v111
	v_exp_f32_e32 v112, v112
	v_exp_f32_e32 v113, v113
	v_exp_f32_e32 v102, v102
	v_exp_f32_e32 v103, v103
	v_pk_mul_f32 v[100:101], v[104:105], v[100:101]
	v_pk_add_f32 v[104:105], v[120:121], 1.0 op_sel_hi:[1,0]
	v_pk_add_f32 v[110:111], v[110:111], 1.0 op_sel_hi:[1,0]
	v_rcp_f32_e32 v104, v104
	v_rcp_f32_e32 v105, v105
	v_pk_add_f32 v[112:113], v[112:113], 1.0 op_sel_hi:[1,0]
	v_pk_add_f32 v[102:103], v[102:103], 1.0 op_sel_hi:[1,0]
	v_rcp_f32_e32 v110, v110
	v_rcp_f32_e32 v111, v111
	v_rcp_f32_e32 v112, v112
	v_rcp_f32_e32 v113, v113
	v_rcp_f32_e32 v102, v102
	v_rcp_f32_e32 v103, v103
	v_mul_f32_e32 v118, v145, v145
	v_pk_mul_f32 v[106:107], v[106:107], v[118:119] op_sel_hi:[1,0]
	v_pk_mul_f32 v[108:109], v[108:109], v[118:119] op_sel_hi:[1,0]
	v_pk_mul_f32 v[98:99], v[98:99], v[118:119] op_sel_hi:[1,0]
	v_pk_mul_f32 v[100:101], v[100:101], v[118:119] op_sel_hi:[1,0]
	v_pk_mul_f32 v[104:105], v[106:107], v[104:105]
	v_pk_mul_f32 v[106:107], v[108:109], v[110:111]
	v_pk_mul_f32 v[108:109], v[98:99], v[112:113]
	v_pk_mul_f32 v[102:103], v[100:101], v[102:103]
	v_or_b32_e32 v110, 16, v141
	v_cvt_pk_bf16_f32 v98, v104, v105
	ds_read2_b32 v[104:105], v142 offset0:32 offset1:48
	v_cvt_pk_bf16_f32 v101, v102, v103
	v_mad_i64_i32 v[102:103], s[16:17], v110, s7, v[114:115]
	v_lshl_add_u64 v[102:103], v[102:103], 0, s[14:15]
	v_lshl_add_u64 v[102:103], v[102:103], 0, s[96:97]
	v_lshl_add_u64 v[102:103], v[102:103], 0, v[190:191]
	v_cvt_pk_bf16_f32 v99, v106, v107
	v_cvt_pk_bf16_f32 v100, v108, v109
	global_store_dwordx4 v[102:103], v[98:101], off
	v_pk_mul_f32 v[92:93], v[96:97], v[92:93]
	v_pk_mul_f32 v[90:91], v[94:95], v[90:91]
	s_waitcnt lgkmcnt(0)
	v_mul_f32_e32 v98, 0xbfb8aa3b, v104
	v_pk_mul_f32 v[102:103], v[94:95], v[98:99] op_sel_hi:[1,0]
	v_pk_mul_f32 v[94:95], v[96:97], v[98:99] op_sel_hi:[1,0]
	v_pk_mul_f32 v[96:97], v[86:87], v[98:99] op_sel_hi:[1,0]
	v_pk_mul_f32 v[82:83], v[86:87], v[82:83]
	v_pk_mul_f32 v[86:87], v[88:89], v[98:99] op_sel_hi:[1,0]
	v_exp_f32_e32 v102, v102
	v_exp_f32_e32 v103, v103
	v_exp_f32_e32 v94, v94
	v_exp_f32_e32 v95, v95
	v_exp_f32_e32 v86, v86
	v_exp_f32_e32 v87, v87
	v_exp_f32_e32 v96, v96
	v_exp_f32_e32 v97, v97
	v_pk_mul_f32 v[84:85], v[88:89], v[84:85]
	v_pk_add_f32 v[88:89], v[102:103], 1.0 op_sel_hi:[1,0]
	v_pk_add_f32 v[94:95], v[94:95], 1.0 op_sel_hi:[1,0]
	v_pk_add_f32 v[86:87], v[86:87], 1.0 op_sel_hi:[1,0]
	v_rcp_f32_e32 v88, v88
	v_rcp_f32_e32 v89, v89
	v_rcp_f32_e32 v94, v94
	v_rcp_f32_e32 v95, v95
	v_rcp_f32_e32 v86, v86
	v_rcp_f32_e32 v87, v87
	v_mul_f32_e32 v100, v104, v104
	v_pk_mul_f32 v[90:91], v[90:91], v[100:101] op_sel_hi:[1,0]
	v_pk_mul_f32 v[92:93], v[92:93], v[100:101] op_sel_hi:[1,0]
	v_pk_mul_f32 v[84:85], v[84:85], v[100:101] op_sel_hi:[1,0]
	v_pk_add_f32 v[96:97], v[96:97], 1.0 op_sel_hi:[1,0]
	v_pk_mul_f32 v[88:89], v[90:91], v[88:89]
	v_rcp_f32_e32 v96, v96
	v_rcp_f32_e32 v97, v97
	v_pk_mul_f32 v[90:91], v[92:93], v[94:95]
	v_pk_mul_f32 v[86:87], v[84:85], v[86:87]
	v_or_b32_e32 v94, 32, v141
	v_cvt_pk_bf16_f32 v85, v86, v87
	v_mad_i64_i32 v[86:87], s[16:17], v94, s7, v[114:115]
	v_lshl_add_u64 v[86:87], v[86:87], 0, s[14:15]
	v_pk_mul_f32 v[82:83], v[82:83], v[100:101] op_sel_hi:[1,0]
	v_lshl_add_u64 v[86:87], v[86:87], 0, s[96:97]
	v_pk_mul_f32 v[92:93], v[82:83], v[96:97]
	v_cvt_pk_bf16_f32 v82, v88, v89
	v_lshl_add_u64 v[86:87], v[86:87], 0, v[190:191]
	v_cvt_pk_bf16_f32 v83, v90, v91
	v_cvt_pk_bf16_f32 v84, v92, v93
	global_store_dwordx4 v[86:87], v[82:85], off
	v_pk_mul_f32 v[76:77], v[80:81], v[76:77]
	v_pk_mul_f32 v[74:75], v[78:79], v[74:75]
	v_mul_f32_e32 v82, 0xbfb8aa3b, v105
	v_pk_mul_f32 v[86:87], v[78:79], v[82:83] op_sel_hi:[1,0]
	v_pk_mul_f32 v[78:79], v[80:81], v[82:83] op_sel_hi:[1,0]
	v_exp_f32_e32 v86, v86
	v_exp_f32_e32 v87, v87
	v_pk_mul_f32 v[80:81], v[70:71], v[82:83] op_sel_hi:[1,0]
	v_pk_mul_f32 v[66:67], v[70:71], v[66:67]
	v_pk_mul_f32 v[70:71], v[72:73], v[82:83] op_sel_hi:[1,0]
	v_exp_f32_e32 v78, v78
	v_exp_f32_e32 v79, v79
	v_exp_f32_e32 v80, v80
	v_exp_f32_e32 v81, v81
	v_exp_f32_e32 v70, v70
	v_exp_f32_e32 v71, v71
	v_pk_mul_f32 v[68:69], v[72:73], v[68:69]
	v_pk_add_f32 v[72:73], v[86:87], 1.0 op_sel_hi:[1,0]
	v_pk_add_f32 v[78:79], v[78:79], 1.0 op_sel_hi:[1,0]
	v_rcp_f32_e32 v72, v72
	v_rcp_f32_e32 v73, v73
	v_pk_add_f32 v[80:81], v[80:81], 1.0 op_sel_hi:[1,0]
	v_pk_add_f32 v[70:71], v[70:71], 1.0 op_sel_hi:[1,0]
	v_rcp_f32_e32 v78, v78
	v_rcp_f32_e32 v79, v79
	v_rcp_f32_e32 v80, v80
	v_rcp_f32_e32 v81, v81
	v_rcp_f32_e32 v70, v70
	v_rcp_f32_e32 v71, v71
	v_mul_f32_e32 v84, v105, v105
	v_pk_mul_f32 v[74:75], v[74:75], v[84:85] op_sel_hi:[1,0]
	v_pk_mul_f32 v[76:77], v[76:77], v[84:85] op_sel_hi:[1,0]
	v_pk_mul_f32 v[66:67], v[66:67], v[84:85] op_sel_hi:[1,0]
	v_pk_mul_f32 v[68:69], v[68:69], v[84:85] op_sel_hi:[1,0]
	v_pk_mul_f32 v[72:73], v[74:75], v[72:73]
	v_pk_mul_f32 v[74:75], v[76:77], v[78:79]
	v_pk_mul_f32 v[76:77], v[66:67], v[80:81]
	v_pk_mul_f32 v[70:71], v[68:69], v[70:71]
	v_or_b32_e32 v78, 48, v141
	v_cvt_pk_bf16_f32 v66, v72, v73
	ds_read2_b32 v[72:73], v142 offset0:128 offset1:144
	v_cvt_pk_bf16_f32 v69, v70, v71
	v_mad_i64_i32 v[70:71], s[16:17], v78, s7, v[114:115]
	v_lshl_add_u64 v[70:71], v[70:71], 0, s[14:15]
	v_lshl_add_u64 v[70:71], v[70:71], 0, s[96:97]
	v_cvt_pk_bf16_f32 v67, v74, v75
	v_lshl_add_u64 v[70:71], v[70:71], 0, v[190:191]
	v_cvt_pk_bf16_f32 v68, v76, v77
	global_store_dwordx4 v[70:71], v[66:69], off
	v_pk_mul_f32 v[60:61], v[64:65], v[60:61]
	v_pk_mul_f32 v[58:59], v[62:63], v[58:59]
	v_add_u32_e32 v67, 0x80, v141
	s_waitcnt lgkmcnt(0)
	v_mul_f32_e32 v66, 0xbfb8aa3b, v72
	v_pk_mul_f32 v[70:71], v[62:63], v[66:67] op_sel_hi:[1,0]
	v_pk_mul_f32 v[62:63], v[64:65], v[66:67] op_sel_hi:[1,0]
	v_pk_mul_f32 v[64:65], v[54:55], v[66:67] op_sel_hi:[1,0]
	v_pk_mul_f32 v[50:51], v[54:55], v[50:51]
	v_pk_mul_f32 v[54:55], v[56:57], v[66:67] op_sel_hi:[1,0]
	v_exp_f32_e32 v70, v70
	v_exp_f32_e32 v54, v54
	v_exp_f32_e32 v55, v55
	v_exp_f32_e32 v71, v71
	v_exp_f32_e32 v62, v62
	v_exp_f32_e32 v63, v63
	v_exp_f32_e32 v64, v64
	v_exp_f32_e32 v65, v65
	v_pk_add_f32 v[54:55], v[54:55], 1.0 op_sel_hi:[1,0]
	v_mul_f32_e32 v68, v72, v72
	v_rcp_f32_e32 v54, v54
	v_rcp_f32_e32 v55, v55
	v_pk_mul_f32 v[52:53], v[56:57], v[52:53]
	v_pk_add_f32 v[56:57], v[70:71], 1.0 op_sel_hi:[1,0]
	v_pk_mul_f32 v[52:53], v[52:53], v[68:69] op_sel_hi:[1,0]
	v_pk_add_f32 v[62:63], v[62:63], 1.0 op_sel_hi:[1,0]
	v_pk_add_f32 v[64:65], v[64:65], 1.0 op_sel_hi:[1,0]
	v_rcp_f32_e32 v56, v56
	v_rcp_f32_e32 v57, v57
	v_rcp_f32_e32 v62, v62
	v_rcp_f32_e32 v63, v63
	v_rcp_f32_e32 v64, v64
	v_rcp_f32_e32 v65, v65
	v_pk_mul_f32 v[54:55], v[52:53], v[54:55]
	v_pk_mul_f32 v[58:59], v[58:59], v[68:69] op_sel_hi:[1,0]
	v_cvt_pk_bf16_f32 v53, v54, v55
	v_mad_i64_i32 v[54:55], s[16:17], v67, s7, v[114:115]
	v_lshl_add_u64 v[54:55], v[54:55], 0, s[14:15]
	v_pk_mul_f32 v[60:61], v[60:61], v[68:69] op_sel_hi:[1,0]
	v_pk_mul_f32 v[50:51], v[50:51], v[68:69] op_sel_hi:[1,0]
	v_lshl_add_u64 v[54:55], v[54:55], 0, s[96:97]
	v_pk_mul_f32 v[56:57], v[58:59], v[56:57]
	v_pk_mul_f32 v[58:59], v[60:61], v[62:63]
	v_pk_mul_f32 v[60:61], v[50:51], v[64:65]
	v_cvt_pk_bf16_f32 v50, v56, v57
	v_lshl_add_u64 v[54:55], v[54:55], 0, v[190:191]
	v_cvt_pk_bf16_f32 v51, v58, v59
	v_cvt_pk_bf16_f32 v52, v60, v61
	global_store_dwordx4 v[54:55], v[50:53], off
	v_pk_mul_f32 v[44:45], v[48:49], v[44:45]
	v_pk_mul_f32 v[42:43], v[46:47], v[42:43]
	v_mul_f32_e32 v50, 0xbfb8aa3b, v73
	v_pk_mul_f32 v[54:55], v[46:47], v[50:51] op_sel_hi:[1,0]
	v_pk_mul_f32 v[46:47], v[48:49], v[50:51] op_sel_hi:[1,0]
	v_exp_f32_e32 v54, v54
	v_exp_f32_e32 v55, v55
	v_pk_mul_f32 v[48:49], v[38:39], v[50:51] op_sel_hi:[1,0]
	v_pk_mul_f32 v[34:35], v[38:39], v[34:35]
	v_pk_mul_f32 v[38:39], v[40:41], v[50:51] op_sel_hi:[1,0]
	v_exp_f32_e32 v46, v46
	v_exp_f32_e32 v47, v47
	v_exp_f32_e32 v48, v48
	v_exp_f32_e32 v49, v49
	v_exp_f32_e32 v38, v38
	v_exp_f32_e32 v39, v39
	v_pk_mul_f32 v[36:37], v[40:41], v[36:37]
	v_pk_add_f32 v[40:41], v[54:55], 1.0 op_sel_hi:[1,0]
	v_pk_add_f32 v[46:47], v[46:47], 1.0 op_sel_hi:[1,0]
	v_rcp_f32_e32 v40, v40
	v_rcp_f32_e32 v41, v41
	v_pk_add_f32 v[48:49], v[48:49], 1.0 op_sel_hi:[1,0]
	v_pk_add_f32 v[38:39], v[38:39], 1.0 op_sel_hi:[1,0]
	v_rcp_f32_e32 v46, v46
	v_rcp_f32_e32 v47, v47
	v_rcp_f32_e32 v48, v48
	v_rcp_f32_e32 v49, v49
	v_rcp_f32_e32 v38, v38
	v_rcp_f32_e32 v39, v39
	v_mul_f32_e32 v52, v73, v73
	v_pk_mul_f32 v[42:43], v[42:43], v[52:53] op_sel_hi:[1,0]
	v_pk_mul_f32 v[44:45], v[44:45], v[52:53] op_sel_hi:[1,0]
	v_pk_mul_f32 v[34:35], v[34:35], v[52:53] op_sel_hi:[1,0]
	v_pk_mul_f32 v[36:37], v[36:37], v[52:53] op_sel_hi:[1,0]
	v_pk_mul_f32 v[40:41], v[42:43], v[40:41]
	v_pk_mul_f32 v[42:43], v[44:45], v[46:47]
	v_pk_mul_f32 v[44:45], v[34:35], v[48:49]
	v_pk_mul_f32 v[38:39], v[36:37], v[38:39]
	v_add_u32_e32 v46, 0x90, v141
	v_cvt_pk_bf16_f32 v34, v40, v41
	ds_read2_b32 v[40:41], v142 offset0:160 offset1:176
	v_cvt_pk_bf16_f32 v37, v38, v39
	v_mad_i64_i32 v[38:39], s[16:17], v46, s7, v[114:115]
	v_lshl_add_u64 v[38:39], v[38:39], 0, s[14:15]
	v_lshl_add_u64 v[38:39], v[38:39], 0, s[96:97]
	v_lshl_add_u64 v[38:39], v[38:39], 0, v[190:191]
	v_cvt_pk_bf16_f32 v35, v42, v43
	v_cvt_pk_bf16_f32 v36, v44, v45
	global_store_dwordx4 v[38:39], v[34:37], off
	v_pk_mul_f32 v[28:29], v[32:33], v[28:29]
	v_pk_mul_f32 v[26:27], v[30:31], v[26:27]
	s_waitcnt lgkmcnt(0)
	v_mul_f32_e32 v34, 0xbfb8aa3b, v40
	v_pk_mul_f32 v[38:39], v[30:31], v[34:35] op_sel_hi:[1,0]
	v_pk_mul_f32 v[30:31], v[32:33], v[34:35] op_sel_hi:[1,0]
	v_pk_mul_f32 v[32:33], v[22:23], v[34:35] op_sel_hi:[1,0]
	v_pk_mul_f32 v[18:19], v[22:23], v[18:19]
	v_pk_mul_f32 v[22:23], v[24:25], v[34:35] op_sel_hi:[1,0]
	v_exp_f32_e32 v38, v38
	v_exp_f32_e32 v39, v39
	v_exp_f32_e32 v30, v30
	v_exp_f32_e32 v31, v31
	v_exp_f32_e32 v22, v22
	v_exp_f32_e32 v23, v23
	v_exp_f32_e32 v32, v32
	v_exp_f32_e32 v33, v33
	v_pk_mul_f32 v[20:21], v[24:25], v[20:21]
	v_pk_add_f32 v[24:25], v[38:39], 1.0 op_sel_hi:[1,0]
	v_pk_add_f32 v[30:31], v[30:31], 1.0 op_sel_hi:[1,0]
	v_pk_add_f32 v[22:23], v[22:23], 1.0 op_sel_hi:[1,0]
	v_rcp_f32_e32 v24, v24
	v_rcp_f32_e32 v25, v25
	v_rcp_f32_e32 v30, v30
	v_rcp_f32_e32 v31, v31
	v_rcp_f32_e32 v22, v22
	v_rcp_f32_e32 v23, v23
	v_mul_f32_e32 v36, v40, v40
	v_pk_mul_f32 v[26:27], v[26:27], v[36:37] op_sel_hi:[1,0]
	v_pk_mul_f32 v[28:29], v[28:29], v[36:37] op_sel_hi:[1,0]
	v_pk_mul_f32 v[20:21], v[20:21], v[36:37] op_sel_hi:[1,0]
	v_pk_add_f32 v[32:33], v[32:33], 1.0 op_sel_hi:[1,0]
	v_pk_mul_f32 v[24:25], v[26:27], v[24:25]
	v_rcp_f32_e32 v32, v32
	v_rcp_f32_e32 v33, v33
	v_pk_mul_f32 v[26:27], v[28:29], v[30:31]
	v_pk_mul_f32 v[22:23], v[20:21], v[22:23]
	v_add_u32_e32 v30, 0xa0, v141
	v_cvt_pk_bf16_f32 v21, v22, v23
	v_mad_i64_i32 v[22:23], s[16:17], v30, s7, v[114:115]
	v_lshl_add_u64 v[22:23], v[22:23], 0, s[14:15]
	v_pk_mul_f32 v[18:19], v[18:19], v[36:37] op_sel_hi:[1,0]
	v_lshl_add_u64 v[22:23], v[22:23], 0, s[96:97]
	v_pk_mul_f32 v[28:29], v[18:19], v[32:33]
	v_cvt_pk_bf16_f32 v18, v24, v25
	v_lshl_add_u64 v[22:23], v[22:23], 0, v[190:191]
	v_cvt_pk_bf16_f32 v19, v26, v27
	v_cvt_pk_bf16_f32 v20, v28, v29
	global_store_dwordx4 v[22:23], v[18:21], off
	v_pk_mul_f32 v[12:13], v[16:17], v[12:13]
	v_pk_mul_f32 v[10:11], v[14:15], v[10:11]
	v_mul_f32_e32 v18, 0xbfb8aa3b, v41
	v_pk_mul_f32 v[22:23], v[14:15], v[18:19] op_sel_hi:[1,0]
	v_pk_mul_f32 v[14:15], v[16:17], v[18:19] op_sel_hi:[1,0]
	v_pk_mul_f32 v[16:17], v[6:7], v[18:19] op_sel_hi:[1,0]
	v_pk_mul_f32 v[2:3], v[6:7], v[2:3]
	v_pk_mul_f32 v[6:7], v[8:9], v[18:19] op_sel_hi:[1,0]
	v_exp_f32_e32 v22, v22
	v_exp_f32_e32 v23, v23
	v_exp_f32_e32 v14, v14
	v_exp_f32_e32 v15, v15
	v_exp_f32_e32 v6, v6
	v_exp_f32_e32 v7, v7
	v_pk_mul_f32 v[4:5], v[8:9], v[4:5]
	v_pk_add_f32 v[8:9], v[22:23], 1.0 op_sel_hi:[1,0]
	v_pk_add_f32 v[14:15], v[14:15], 1.0 op_sel_hi:[1,0]
	v_pk_add_f32 v[6:7], v[6:7], 1.0 op_sel_hi:[1,0]
	v_exp_f32_e32 v16, v16
	v_exp_f32_e32 v17, v17
	v_rcp_f32_e32 v8, v8
	v_rcp_f32_e32 v9, v9
	v_rcp_f32_e32 v14, v14
	v_rcp_f32_e32 v15, v15
	v_rcp_f32_e32 v6, v6
	v_rcp_f32_e32 v7, v7
	v_mul_f32_e32 v20, v41, v41
	v_pk_mul_f32 v[10:11], v[10:11], v[20:21] op_sel_hi:[1,0]
	v_pk_mul_f32 v[12:13], v[12:13], v[20:21] op_sel_hi:[1,0]
	v_pk_mul_f32 v[4:5], v[4:5], v[20:21] op_sel_hi:[1,0]
	v_pk_add_f32 v[16:17], v[16:17], 1.0 op_sel_hi:[1,0]
	v_pk_mul_f32 v[8:9], v[10:11], v[8:9]
	v_pk_mul_f32 v[10:11], v[12:13], v[14:15]
	v_pk_mul_f32 v[6:7], v[4:5], v[6:7]
	v_add_u32_e32 v14, 0xb0, v141
	v_rcp_f32_e32 v16, v16
	v_rcp_f32_e32 v17, v17
	v_cvt_pk_bf16_f32 v5, v6, v7
	v_mad_i64_i32 v[6:7], s[16:17], v14, s7, v[114:115]
	v_lshl_add_u64 v[6:7], v[6:7], 0, s[14:15]
	v_lshl_add_u64 v[6:7], v[6:7], 0, s[96:97]
	v_pk_mul_f32 v[2:3], v[2:3], v[20:21] op_sel_hi:[1,0]
	v_lshl_add_u64 v[6:7], v[6:7], 0, v[190:191]
	s_and_b64 vcc, exec, s[38:39]
	s_mov_b32 s35, s6
	s_mov_b32 s36, s8
	s_mov_b64 s[16:17], s[12:13]
	s_mov_b64 s[14:15], s[10:11]
	s_mov_b32 s37, s34
	v_pk_mul_f32 v[12:13], v[2:3], v[16:17]
	v_cvt_pk_bf16_f32 v2, v8, v9
	v_cvt_pk_bf16_f32 v3, v10, v11
	s_nop 0
	v_cvt_pk_bf16_f32 v4, v12, v13
	global_store_dwordx4 v[6:7], v[2:5], off
	s_cbranch_vccz .LBB0_92
	s_waitcnt vmcnt(0)
	v_readlane_b32 s30, v252, 21
	s_cmpk_gt_u32 s22, 0xff
	v_readlane_b32 s31, v252, 22
	s_mov_b32 s34, 0x800000
	s_movk_i32 s35, 0x4000
	s_movk_i32 s36, 0x90
	s_movk_i32 s37, 0x300
	s_movk_i32 s54, 0x2810
	s_movk_i32 s55, 0xdff
	v_readlane_b32 s56, v252, 31
	s_movk_i32 s57, 0x110
	s_mov_b32 s58, 0x2aaaaaab
	s_movk_i32 s59, 0xffd0
	v_readlane_b32 s76, v252, 46
	s_cbranch_scc1 .LBB0_103
	s_barrier

.LBB0_278:
	s_add_u32 s16, s14, 0xfffc0080
	s_addc_u32 s17, s15, -1
	s_add_i32 s47, 0, 0x10000
	v_add_u32_e32 v249, s47, v203
	ds_read_b128 v[118:121], v249
	ds_read_b128 v[122:125], v249 offset:1024
	ds_read_b128 v[130:133], v249 offset:2048
	ds_read_b128 v[134:137], v249 offset:3072
	s_cmp_eq_u32 s46, 12
	s_cselect_b32 s19, s9, s17
	s_cselect_b32 s18, s36, s16
	s_cselect_b32 s17, s7, s45
	s_cselect_b32 s16, s37, s44
	s_add_i32 m0, s23, 0xc000
	ds_read_b128 v[138:141], v220
	ds_read_b128 v[146:149], v220 offset:1024
	ds_read_b128 v[154:157], v220 offset:2048
	ds_read_b128 v[158:161], v220 offset:3072
	ds_read_b128 v[162:165], v220 offset:4096
	ds_read_b128 v[166:169], v220 offset:5120
	ds_read_b128 v[170:173], v220 offset:6144
	ds_read_b128 v[174:177], v220 offset:7168
	global_load_lds_dwordx4 v212, s[14:15]
	s_add_i32 m0, s23, 0xe000
	s_nop 0
	global_load_lds_dwordx4 v214, s[14:15]
	s_waitcnt lgkmcnt(8)
	s_barrier
	s_waitcnt lgkmcnt(0)
	s_setprio 1
	s_waitcnt lgkmcnt(0)
	v_mfma_f32_16x16x32_bf16 v[150:153], v[118:121], v[138:141], v[150:153]
	v_mfma_f32_16x16x32_bf16 v[142:145], v[130:133], v[138:141], v[142:145]
	v_mfma_f32_16x16x32_bf16 v[110:113], v[118:121], v[154:157], v[110:113]
	v_mfma_f32_16x16x32_bf16 v[106:109], v[130:133], v[154:157], v[106:109]
	v_mfma_f32_16x16x32_bf16 v[94:97], v[118:121], v[162:165], v[94:97]
	v_mfma_f32_16x16x32_bf16 v[90:93], v[130:133], v[162:165], v[90:93]
	v_mfma_f32_16x16x32_bf16 v[78:81], v[118:121], v[170:173], v[78:81]
	v_mfma_f32_16x16x32_bf16 v[74:77], v[130:133], v[170:173], v[74:77]
	v_mfma_f32_16x16x32_bf16 v[150:153], v[122:125], v[146:149], v[150:153]
	v_mfma_f32_16x16x32_bf16 v[142:145], v[134:137], v[146:149], v[142:145]
	v_mfma_f32_16x16x32_bf16 v[110:113], v[122:125], v[158:161], v[110:113]
	v_mfma_f32_16x16x32_bf16 v[106:109], v[134:137], v[158:161], v[106:109]
	v_mfma_f32_16x16x32_bf16 v[94:97], v[122:125], v[166:169], v[94:97]
	v_mfma_f32_16x16x32_bf16 v[90:93], v[134:137], v[166:169], v[90:93]
	v_mfma_f32_16x16x32_bf16 v[78:81], v[122:125], v[174:177], v[78:81]
	v_mfma_f32_16x16x32_bf16 v[74:77], v[134:137], v[174:177], v[74:77]
	s_setprio 0
	s_barrier
	s_add_i32 s50, 0, 0x14000
	s_add_i32 s47, s47, s22
	ds_read_b128 v[178:181], v249 offset:16384
	ds_read_b128 v[182:185], v249 offset:17408
	ds_read_b128 v[186:189], v249 offset:18432
	ds_read_b128 v[216:219], v249 offset:19456
	s_mov_b32 m0, s47
	s_nop 0
	global_load_lds_dwordx4 v208, s[16:17]
	s_add_i32 m0, s47, 0x2000
	s_nop 0
	global_load_lds_dwordx4 v204, s[16:17]
	s_barrier
	s_waitcnt lgkmcnt(0)
	s_setprio 1
	s_waitcnt lgkmcnt(0)
	v_mfma_f32_16x16x32_bf16 v[126:129], v[178:181], v[138:141], v[126:129]
	v_mfma_f32_16x16x32_bf16 v[114:117], v[186:189], v[138:141], v[114:117]
	v_mfma_f32_16x16x32_bf16 v[102:105], v[178:181], v[154:157], v[102:105]
	v_mfma_f32_16x16x32_bf16 v[98:101], v[186:189], v[154:157], v[98:101]
	v_mfma_f32_16x16x32_bf16 v[86:89], v[178:181], v[162:165], v[86:89]
	v_mfma_f32_16x16x32_bf16 v[82:85], v[186:189], v[162:165], v[82:85]
	v_mfma_f32_16x16x32_bf16 v[70:73], v[178:181], v[170:173], v[70:73]
	v_mfma_f32_16x16x32_bf16 v[66:69], v[186:189], v[170:173], v[66:69]
	v_mfma_f32_16x16x32_bf16 v[126:129], v[182:185], v[146:149], v[126:129]
	v_mfma_f32_16x16x32_bf16 v[114:117], v[216:219], v[146:149], v[114:117]
	v_mfma_f32_16x16x32_bf16 v[102:105], v[182:185], v[158:161], v[102:105]
	v_mfma_f32_16x16x32_bf16 v[98:101], v[216:219], v[158:161], v[98:101]
	v_mfma_f32_16x16x32_bf16 v[86:89], v[182:185], v[166:169], v[86:89]
	v_mfma_f32_16x16x32_bf16 v[82:85], v[216:219], v[166:169], v[82:85]
	v_mfma_f32_16x16x32_bf16 v[70:73], v[182:185], v[174:177], v[70:73]
	v_mfma_f32_16x16x32_bf16 v[66:69], v[216:219], v[174:177], v[66:69]
	s_setprio 0
	s_mov_b32 m0, s23
	s_add_u32 s98, s18, 0x80
	s_addc_u32 s99, s19, 0
	s_barrier
	ds_read_b128 v[138:141], v220 offset:16384
	ds_read_b128 v[146:149], v220 offset:17408
	ds_read_b128 v[154:157], v220 offset:18432
	ds_read_b128 v[158:161], v220 offset:19456
	ds_read_b128 v[162:165], v220 offset:20480
	ds_read_b128 v[166:169], v220 offset:21504
	ds_read_b128 v[170:173], v220 offset:22528
	ds_read_b128 v[174:177], v220 offset:23552
	global_load_lds_dwordx4 v210, s[18:19]
	s_mov_b32 m0, s24
	s_nop 0
	global_load_lds_dwordx4 v206, s[18:19]
	s_barrier
	s_waitcnt lgkmcnt(0)
	s_setprio 1
	s_waitcnt lgkmcnt(0)
	v_mfma_f32_16x16x32_bf16 v[62:65], v[118:121], v[138:141], v[62:65]
	v_mfma_f32_16x16x32_bf16 v[58:61], v[130:133], v[138:141], v[58:61]
	v_mfma_f32_16x16x32_bf16 v[46:49], v[118:121], v[154:157], v[46:49]
	v_mfma_f32_16x16x32_bf16 v[42:45], v[130:133], v[154:157], v[42:45]
	v_mfma_f32_16x16x32_bf16 v[30:33], v[118:121], v[162:165], v[30:33]
	v_mfma_f32_16x16x32_bf16 v[26:29], v[130:133], v[162:165], v[26:29]
	v_mfma_f32_16x16x32_bf16 v[14:17], v[118:121], v[170:173], v[14:17]
	v_mfma_f32_16x16x32_bf16 v[10:13], v[130:133], v[170:173], v[10:13]
	v_mfma_f32_16x16x32_bf16 v[62:65], v[122:125], v[146:149], v[62:65]
	v_mfma_f32_16x16x32_bf16 v[58:61], v[134:137], v[146:149], v[58:61]
	v_mfma_f32_16x16x32_bf16 v[46:49], v[122:125], v[158:161], v[46:49]
	v_mfma_f32_16x16x32_bf16 v[42:45], v[134:137], v[158:161], v[42:45]
	v_mfma_f32_16x16x32_bf16 v[30:33], v[122:125], v[166:169], v[30:33]
	v_mfma_f32_16x16x32_bf16 v[26:29], v[134:137], v[166:169], v[26:29]
	v_mfma_f32_16x16x32_bf16 v[14:17], v[122:125], v[174:177], v[14:17]
	v_mfma_f32_16x16x32_bf16 v[10:13], v[134:137], v[174:177], v[10:13]
	s_setprio 0
	s_barrier
	s_add_u32 s48, s16, 0x40000
	s_addc_u32 s49, s17, 0
	s_add_i32 s47, s50, s22
	s_mov_b32 m0, s47
	s_nop 0
	global_load_lds_dwordx4 v208, s[48:49]
	s_add_i32 m0, s47, 0x2000
	s_nop 0
	global_load_lds_dwordx4 v204, s[48:49]
	s_waitcnt vmcnt(6)
	s_barrier
	s_setprio 1
	v_mfma_f32_16x16x32_bf16 v[54:57], v[178:181], v[138:141], v[54:57]
	v_mfma_f32_16x16x32_bf16 v[50:53], v[186:189], v[138:141], v[50:53]
	v_mfma_f32_16x16x32_bf16 v[38:41], v[178:181], v[154:157], v[38:41]
	v_mfma_f32_16x16x32_bf16 v[34:37], v[186:189], v[154:157], v[34:37]
	v_mfma_f32_16x16x32_bf16 v[22:25], v[178:181], v[162:165], v[22:25]
	v_mfma_f32_16x16x32_bf16 v[18:21], v[186:189], v[162:165], v[18:21]
	v_mfma_f32_16x16x32_bf16 v[6:9], v[178:181], v[170:173], v[6:9]
	v_mfma_f32_16x16x32_bf16 v[2:5], v[186:189], v[170:173], v[2:5]
	v_mfma_f32_16x16x32_bf16 v[54:57], v[182:185], v[146:149], v[54:57]
	v_mfma_f32_16x16x32_bf16 v[50:53], v[216:219], v[146:149], v[50:53]
	v_mfma_f32_16x16x32_bf16 v[38:41], v[182:185], v[158:161], v[38:41]
	v_mfma_f32_16x16x32_bf16 v[34:37], v[216:219], v[158:161], v[34:37]
	v_mfma_f32_16x16x32_bf16 v[22:25], v[182:185], v[166:169], v[22:25]
	v_mfma_f32_16x16x32_bf16 v[18:21], v[216:219], v[166:169], v[18:21]
	v_mfma_f32_16x16x32_bf16 v[6:9], v[182:185], v[174:177], v[6:9]
	v_mfma_f32_16x16x32_bf16 v[2:5], v[216:219], v[174:177], v[2:5]
	s_setprio 0
	s_add_i32 s47, 0, 0x18000
	s_barrier
	ds_read_b128 v[118:121], v249 offset:32768
	ds_read_b128 v[122:125], v249 offset:33792
	ds_read_b128 v[130:133], v249 offset:34816
	ds_read_b128 v[134:137], v249 offset:35840
	s_add_u32 s18, s18, 0x40000
	s_addc_u32 s19, s19, 0
	s_mov_b32 m0, s25
	ds_read_b128 v[138:141], v220 offset:32768
	ds_read_b128 v[146:149], v220 offset:33792
	ds_read_b128 v[154:157], v220 offset:34816
	ds_read_b128 v[158:161], v220 offset:35840
	ds_read_b128 v[162:165], v220 offset:36864
	ds_read_b128 v[166:169], v220 offset:37888
	ds_read_b128 v[170:173], v220 offset:38912
	ds_read_b128 v[174:177], v220 offset:39936
	global_load_lds_dwordx4 v210, s[18:19]
	s_mov_b32 m0, s26
	s_nop 0
	global_load_lds_dwordx4 v206, s[18:19]
	s_waitcnt lgkmcnt(8)
	s_barrier
	s_waitcnt lgkmcnt(0)
	s_setprio 1
	s_waitcnt lgkmcnt(0)
	v_mfma_f32_16x16x32_bf16 v[150:153], v[118:121], v[138:141], v[150:153]
	v_mfma_f32_16x16x32_bf16 v[142:145], v[130:133], v[138:141], v[142:145]
	v_mfma_f32_16x16x32_bf16 v[110:113], v[118:121], v[154:157], v[110:113]
	v_mfma_f32_16x16x32_bf16 v[106:109], v[130:133], v[154:157], v[106:109]
	v_mfma_f32_16x16x32_bf16 v[94:97], v[118:121], v[162:165], v[94:97]
	v_mfma_f32_16x16x32_bf16 v[90:93], v[130:133], v[162:165], v[90:93]
	v_mfma_f32_16x16x32_bf16 v[78:81], v[118:121], v[170:173], v[78:81]
	v_mfma_f32_16x16x32_bf16 v[74:77], v[130:133], v[170:173], v[74:77]
	v_mfma_f32_16x16x32_bf16 v[150:153], v[122:125], v[146:149], v[150:153]
	v_mfma_f32_16x16x32_bf16 v[142:145], v[134:137], v[146:149], v[142:145]
	v_mfma_f32_16x16x32_bf16 v[110:113], v[122:125], v[158:161], v[110:113]
	v_mfma_f32_16x16x32_bf16 v[106:109], v[134:137], v[158:161], v[106:109]
	v_mfma_f32_16x16x32_bf16 v[94:97], v[122:125], v[166:169], v[94:97]
	v_mfma_f32_16x16x32_bf16 v[90:93], v[134:137], v[166:169], v[90:93]
	v_mfma_f32_16x16x32_bf16 v[78:81], v[122:125], v[174:177], v[78:81]
	v_mfma_f32_16x16x32_bf16 v[74:77], v[134:137], v[174:177], v[74:77]
	s_setprio 0
	s_barrier
	s_add_i32 s18, 0, 0x1c000
	s_add_i32 s19, s47, s22
	s_add_u32 vcc_lo, s16, 0x80
	s_addc_u32 vcc_hi, s17, 0
	s_mov_b32 m0, s19
	ds_read_b128 v[178:181], v249 offset:49152
	ds_read_b128 v[182:185], v249 offset:50176
	ds_read_b128 v[186:189], v249 offset:51200
	ds_read_b128 v[216:219], v249 offset:52224
	global_load_lds_dwordx4 v208, vcc
	s_add_i32 m0, s19, 0x2000
	s_nop 0
	global_load_lds_dwordx4 v204, vcc
	s_barrier
	s_waitcnt lgkmcnt(0)
	s_setprio 1
	s_waitcnt lgkmcnt(0)
	v_mfma_f32_16x16x32_bf16 v[126:129], v[178:181], v[138:141], v[126:129]
	v_mfma_f32_16x16x32_bf16 v[114:117], v[186:189], v[138:141], v[114:117]
	v_mfma_f32_16x16x32_bf16 v[102:105], v[178:181], v[154:157], v[102:105]
	v_mfma_f32_16x16x32_bf16 v[98:101], v[186:189], v[154:157], v[98:101]
	v_mfma_f32_16x16x32_bf16 v[86:89], v[178:181], v[162:165], v[86:89]
	v_mfma_f32_16x16x32_bf16 v[82:85], v[186:189], v[162:165], v[82:85]
	v_mfma_f32_16x16x32_bf16 v[70:73], v[178:181], v[170:173], v[70:73]
	v_mfma_f32_16x16x32_bf16 v[66:69], v[186:189], v[170:173], v[66:69]
	v_mfma_f32_16x16x32_bf16 v[126:129], v[182:185], v[146:149], v[126:129]
	v_mfma_f32_16x16x32_bf16 v[114:117], v[216:219], v[146:149], v[114:117]
	v_mfma_f32_16x16x32_bf16 v[102:105], v[182:185], v[158:161], v[102:105]
	v_mfma_f32_16x16x32_bf16 v[98:101], v[216:219], v[158:161], v[98:101]
	v_mfma_f32_16x16x32_bf16 v[86:89], v[182:185], v[166:169], v[86:89]
	v_mfma_f32_16x16x32_bf16 v[82:85], v[216:219], v[166:169], v[82:85]
	v_mfma_f32_16x16x32_bf16 v[70:73], v[182:185], v[174:177], v[70:73]
	v_mfma_f32_16x16x32_bf16 v[66:69], v[216:219], v[174:177], v[66:69]
	s_setprio 0
	s_mov_b32 m0, s28
	s_barrier
	ds_read_b128 v[138:141], v220 offset:49152
	ds_read_b128 v[146:149], v220 offset:50176
	ds_read_b128 v[154:157], v220 offset:51200
	ds_read_b128 v[158:161], v220 offset:52224
	ds_read_b128 v[162:165], v220 offset:53248
	ds_read_b128 v[166:169], v220 offset:54272
	ds_read_b128 v[170:173], v220 offset:55296
	ds_read_b128 v[174:177], v220 offset:56320
	global_load_lds_dwordx4 v210, s[98:99]
	s_mov_b32 m0, s29
	s_nop 0
	global_load_lds_dwordx4 v206, s[98:99]
	s_barrier
	s_waitcnt lgkmcnt(0)
	s_setprio 1
	s_waitcnt lgkmcnt(0)
	v_mfma_f32_16x16x32_bf16 v[62:65], v[118:121], v[138:141], v[62:65]
	v_mfma_f32_16x16x32_bf16 v[58:61], v[130:133], v[138:141], v[58:61]
	v_mfma_f32_16x16x32_bf16 v[46:49], v[118:121], v[154:157], v[46:49]
	v_mfma_f32_16x16x32_bf16 v[42:45], v[130:133], v[154:157], v[42:45]
	v_mfma_f32_16x16x32_bf16 v[30:33], v[118:121], v[162:165], v[30:33]
	v_mfma_f32_16x16x32_bf16 v[26:29], v[130:133], v[162:165], v[26:29]
	v_mfma_f32_16x16x32_bf16 v[14:17], v[118:121], v[170:173], v[14:17]
	v_mfma_f32_16x16x32_bf16 v[10:13], v[130:133], v[170:173], v[10:13]
	v_mfma_f32_16x16x32_bf16 v[62:65], v[122:125], v[146:149], v[62:65]
	v_mfma_f32_16x16x32_bf16 v[58:61], v[134:137], v[146:149], v[58:61]
	v_mfma_f32_16x16x32_bf16 v[46:49], v[122:125], v[158:161], v[46:49]
	v_mfma_f32_16x16x32_bf16 v[42:45], v[134:137], v[158:161], v[42:45]
	v_mfma_f32_16x16x32_bf16 v[30:33], v[122:125], v[166:169], v[30:33]
	v_mfma_f32_16x16x32_bf16 v[26:29], v[134:137], v[166:169], v[26:29]
	v_mfma_f32_16x16x32_bf16 v[14:17], v[122:125], v[174:177], v[14:17]
	v_mfma_f32_16x16x32_bf16 v[10:13], v[134:137], v[174:177], v[10:13]
	s_setprio 0
	s_barrier
	s_add_u32 s16, s16, 0x40080
	s_addc_u32 s17, s17, 0
	s_add_i32 s18, s18, s22
	s_mov_b32 m0, s18
	s_nop 0
	global_load_lds_dwordx4 v208, s[16:17]
	s_add_i32 m0, s18, 0x2000
	s_nop 0
	global_load_lds_dwordx4 v204, s[16:17]
	s_waitcnt vmcnt(6)
	s_barrier
	s_setprio 1
	v_mfma_f32_16x16x32_bf16 v[54:57], v[178:181], v[138:141], v[54:57]
	v_mfma_f32_16x16x32_bf16 v[50:53], v[186:189], v[138:141], v[50:53]
	v_mfma_f32_16x16x32_bf16 v[38:41], v[178:181], v[154:157], v[38:41]
	v_mfma_f32_16x16x32_bf16 v[34:37], v[186:189], v[154:157], v[34:37]
	v_mfma_f32_16x16x32_bf16 v[22:25], v[178:181], v[162:165], v[22:25]
	v_mfma_f32_16x16x32_bf16 v[18:21], v[186:189], v[162:165], v[18:21]
	v_mfma_f32_16x16x32_bf16 v[6:9], v[178:181], v[170:173], v[6:9]
	v_mfma_f32_16x16x32_bf16 v[2:5], v[186:189], v[170:173], v[2:5]
	v_mfma_f32_16x16x32_bf16 v[54:57], v[182:185], v[146:149], v[54:57]
	v_mfma_f32_16x16x32_bf16 v[50:53], v[216:219], v[146:149], v[50:53]
	v_mfma_f32_16x16x32_bf16 v[38:41], v[182:185], v[158:161], v[38:41]
	v_mfma_f32_16x16x32_bf16 v[34:37], v[216:219], v[158:161], v[34:37]
	v_mfma_f32_16x16x32_bf16 v[22:25], v[182:185], v[166:169], v[22:25]
	v_mfma_f32_16x16x32_bf16 v[18:21], v[216:219], v[166:169], v[18:21]
	v_mfma_f32_16x16x32_bf16 v[6:9], v[182:185], v[174:177], v[6:9]
	v_mfma_f32_16x16x32_bf16 v[2:5], v[216:219], v[174:177], v[2:5]
	s_setprio 0
	s_add_i32 s46, s46, 2
	s_add_u32 s14, s14, 0x100
	s_addc_u32 s15, s15, 0
	s_add_u32 s44, s44, 0x100
	s_addc_u32 s45, s45, 0
	s_cmp_gt_u32 s46, 13
	s_barrier
	s_cbranch_scc0 .LBB0_278
	v_lshl_add_u32 v216, s35, 8, v199
	v_ashrrev_i32_e32 v217, 31, v216
	v_readlane_b32 s14, v252, 51
	v_lshlrev_b64 v[118:119], 11, v[216:217]
	v_readlane_b32 s15, v252, 52
	s_mov_b32 s7, 0x8000
	s_nop 0
	v_lshl_add_u64 v[118:119], s[14:15], 0, v[118:119]
	s_lshl_b32 s14, s34, 8
	s_ashr_i32 s15, s14, 31
	v_lshl_add_u64 v[118:119], s[14:15], 1, v[118:119]
	v_lshl_add_u64 v[118:119], v[118:119], 0, s[96:97]
	v_lshl_add_u64 v[218:219], v[118:119], 0, v[190:191]
	global_load_dwordx4 v[222:225], v[218:219], off
	global_load_dwordx4 v[186:189], v[218:219], off offset:256
	v_add_co_u32_e32 v118, vcc, s7, v218
	s_mov_b32 s7, 0x10000
	s_nop 0
	v_addc_co_u32_e32 v119, vcc, 0, v219, vcc
	global_load_dwordx4 v[182:185], v[118:119], off
	global_load_dwordx4 v[178:181], v[118:119], off offset:256
	v_add_co_u32_e32 v118, vcc, s7, v218
	s_mov_b32 s7, 0x18000
	s_nop 0
	v_addc_co_u32_e32 v119, vcc, 0, v219, vcc
	global_load_dwordx4 v[174:177], v[118:119], off
	global_load_dwordx4 v[170:173], v[118:119], off offset:256
	v_add_co_u32_e32 v118, vcc, s7, v218
	s_mov_b32 s7, 0x58000
	s_nop 0
	v_addc_co_u32_e32 v119, vcc, 0, v219, vcc
	global_load_dwordx4 v[166:169], v[118:119], off
	global_load_dwordx4 v[162:165], v[118:119], off offset:256
	v_add_co_u32_e32 v118, vcc, s51, v218
	s_lshl_b32 s14, s34, 2
	s_nop 0
	v_addc_co_u32_e32 v119, vcc, 0, v219, vcc
	global_load_dwordx4 v[158:161], v[118:119], off
	global_load_dwordx4 v[154:157], v[118:119], off offset:256
	v_add_co_u32_e32 v118, vcc, s54, v218
	s_ashr_i32 s15, s14, 31
	s_nop 0
	v_addc_co_u32_e32 v119, vcc, 0, v219, vcc
	global_load_dwordx4 v[146:149], v[118:119], off
	global_load_dwordx4 v[138:141], v[118:119], off offset:256
	v_add_co_u32_e32 v118, vcc, s55, v218
	s_waitcnt vmcnt(0)
	v_lshlrev_b32_e32 v192, 16, v222
	v_addc_co_u32_e32 v119, vcc, 0, v219, vcc
	global_load_dwordx4 v[134:137], v[118:119], off
	global_load_dwordx4 v[130:133], v[118:119], off offset:256
	v_add_co_u32_e32 v118, vcc, s7, v218
	v_add_f32_e32 v150, v150, v192
	s_nop 0
	v_addc_co_u32_e32 v119, vcc, 0, v219, vcc
	global_load_dwordx4 v[122:125], v[118:119], off
	s_nop 0
	global_load_dwordx4 v[118:121], v[118:119], off offset:256
	v_and_b32_e32 v192, 0xffff0000, v222
	v_add_f32_e32 v151, v151, v192
	v_lshlrev_b32_e32 v192, 16, v223
	v_mul_f32_e32 v195, v151, v151
	v_add_f32_e32 v152, v152, v192
	v_and_b32_e32 v192, 0xffff0000, v223
	v_fmac_f32_e32 v195, v150, v150
	v_add_f32_e32 v153, v153, v192
	v_lshlrev_b32_e32 v192, 16, v224
	v_fmac_f32_e32 v195, v152, v152
	v_add_f32_e32 v192, v142, v192
	v_and_b32_e32 v142, 0xffff0000, v224
	v_fmac_f32_e32 v195, v153, v153
	v_add_f32_e32 v193, v143, v142
	v_lshlrev_b32_e32 v142, 16, v225
	v_fmac_f32_e32 v195, v192, v192
	v_add_f32_e32 v194, v144, v142
	v_and_b32_e32 v142, 0xffff0000, v225
	v_fmac_f32_e32 v195, v193, v193
	v_add_f32_e32 v145, v145, v142
	v_fmac_f32_e32 v195, v194, v194
	v_cvt_pk_bf16_f32 v142, v150, v151
	v_fmac_f32_e32 v195, v145, v145
	v_cvt_pk_bf16_f32 v143, v152, v153
	v_cvt_pk_bf16_f32 v144, v192, v193
	v_cvt_pk_bf16_f32 v145, v194, v145
	global_store_dwordx4 v[218:219], v[142:145], off
	s_nop 1
	v_lshlrev_b32_e32 v142, 16, v186
	v_add_f32_e32 v126, v126, v142
	v_and_b32_e32 v142, 0xffff0000, v186
	v_add_f32_e32 v127, v127, v142
	v_lshlrev_b32_e32 v142, 16, v187
	v_fmac_f32_e32 v195, v126, v126
	v_add_f32_e32 v128, v128, v142
	v_and_b32_e32 v142, 0xffff0000, v187
	v_fmac_f32_e32 v195, v127, v127
	v_add_f32_e32 v129, v129, v142
	v_lshlrev_b32_e32 v142, 16, v188
	v_fmac_f32_e32 v195, v128, v128
	v_add_f32_e32 v142, v114, v142
	v_and_b32_e32 v114, 0xffff0000, v188
	v_fmac_f32_e32 v195, v129, v129
	v_add_f32_e32 v143, v115, v114
	v_lshlrev_b32_e32 v114, 16, v189
	v_fmac_f32_e32 v195, v142, v142
	v_add_f32_e32 v144, v116, v114
	v_and_b32_e32 v114, 0xffff0000, v189
	v_fmac_f32_e32 v195, v143, v143
	v_add_f32_e32 v117, v117, v114
	v_fmac_f32_e32 v195, v144, v144
	v_cvt_pk_bf16_f32 v115, v128, v129
	v_fmac_f32_e32 v195, v117, v117
	v_cvt_pk_bf16_f32 v114, v126, v127
	v_cvt_pk_bf16_f32 v116, v142, v143
	v_cvt_pk_bf16_f32 v117, v144, v117
	global_store_dwordx4 v[218:219], v[114:117], off offset:256
	s_nop 1
	v_and_b32_e32 v115, 64, v244
	v_xor_b32_e32 v114, 16, v244
	v_add_u32_e32 v115, 64, v115
	v_cmp_lt_i32_e32 vcc, v114, v115
	v_xor_b32_e32 v117, 32, v244
	s_nop 0
	v_cndmask_b32_e32 v114, v244, v114, vcc
	v_lshlrev_b32_e32 v114, 2, v114
	ds_bpermute_b32 v116, v114, v195
	v_cmp_lt_i32_e32 vcc, v117, v115
	s_waitcnt lgkmcnt(0)
	v_add_f32_e32 v116, v195, v116
	v_cndmask_b32_e32 v115, v244, v117, vcc
	v_lshlrev_b32_e32 v115, 2, v115
	ds_bpermute_b32 v117, v115, v116
	s_and_saveexec_b64 s[16:17], s[40:41]
	s_cbranch_execz .LBB0_281
	v_readlane_b32 s18, v252, 53
	s_waitcnt lgkmcnt(0)
	v_add_f32_e32 v126, v116, v117
	v_lshlrev_b64 v[116:117], 6, v[216:217]
	v_readlane_b32 s19, v252, 54
	s_nop 1
	v_lshl_add_u64 v[116:117], s[18:19], 0, v[116:117]
	v_lshl_add_u64 v[116:117], s[14:15], 2, v[116:117]
	s_lshl_b32 s18, s27, 2
	s_mov_b32 s19, s97
	v_lshl_add_u64 v[116:117], v[116:117], 0, s[18:19]
	global_store_dword v[116:117], v126, off

.LBB0_1103:
	s_add_u32 s10, s8, 0x100
	s_addc_u32 s11, s9, 0
	s_add_i32 s37, 0, 0x10000
	v_add_u32_e32 v249, s37, v203
	ds_read_b128 v[118:121], v249
	ds_read_b128 v[122:125], v249 offset:1024
	ds_read_b128 v[130:133], v249 offset:2048
	ds_read_b128 v[134:137], v249 offset:3072
	s_cmp_eq_u32 s36, 40
	s_cselect_b32 s15, s1, s11
	s_cselect_b32 s14, s0, s10
	s_cselect_b32 s13, s3, s35
	s_cselect_b32 s12, s2, s34
	s_add_i32 m0, s19, 0xc000
	ds_read_b128 v[138:141], v220
	ds_read_b128 v[146:149], v220 offset:1024
	ds_read_b128 v[154:157], v220 offset:2048
	ds_read_b128 v[158:161], v220 offset:3072
	ds_read_b128 v[162:165], v220 offset:4096
	ds_read_b128 v[166:169], v220 offset:5120
	ds_read_b128 v[170:173], v220 offset:6144
	ds_read_b128 v[174:177], v220 offset:7168
	global_load_lds_dwordx4 v212, s[8:9]
	s_add_i32 m0, s19, 0xe000
	s_nop 0
	global_load_lds_dwordx4 v214, s[8:9]
	s_waitcnt lgkmcnt(8)
	s_barrier
	s_waitcnt lgkmcnt(0)
	s_setprio 1
	s_waitcnt lgkmcnt(0)
	v_mfma_f32_16x16x32_bf16 v[150:153], v[118:121], v[138:141], v[150:153]
	v_mfma_f32_16x16x32_bf16 v[142:145], v[130:133], v[138:141], v[142:145]
	v_mfma_f32_16x16x32_bf16 v[110:113], v[118:121], v[154:157], v[110:113]
	v_mfma_f32_16x16x32_bf16 v[106:109], v[130:133], v[154:157], v[106:109]
	v_mfma_f32_16x16x32_bf16 v[94:97], v[118:121], v[162:165], v[94:97]
	v_mfma_f32_16x16x32_bf16 v[90:93], v[130:133], v[162:165], v[90:93]
	v_mfma_f32_16x16x32_bf16 v[78:81], v[118:121], v[170:173], v[78:81]
	v_mfma_f32_16x16x32_bf16 v[74:77], v[130:133], v[170:173], v[74:77]
	v_mfma_f32_16x16x32_bf16 v[150:153], v[122:125], v[146:149], v[150:153]
	v_mfma_f32_16x16x32_bf16 v[142:145], v[134:137], v[146:149], v[142:145]
	v_mfma_f32_16x16x32_bf16 v[110:113], v[122:125], v[158:161], v[110:113]
	v_mfma_f32_16x16x32_bf16 v[106:109], v[134:137], v[158:161], v[106:109]
	v_mfma_f32_16x16x32_bf16 v[94:97], v[122:125], v[166:169], v[94:97]
	v_mfma_f32_16x16x32_bf16 v[90:93], v[134:137], v[166:169], v[90:93]
	v_mfma_f32_16x16x32_bf16 v[78:81], v[122:125], v[174:177], v[78:81]
	v_mfma_f32_16x16x32_bf16 v[74:77], v[134:137], v[174:177], v[74:77]
	s_setprio 0
	s_barrier
	s_add_i32 s44, 0, 0x14000
	s_add_i32 s8, s37, s18
	ds_read_b128 v[178:181], v249 offset:16384
	ds_read_b128 v[182:185], v249 offset:17408
	ds_read_b128 v[186:189], v249 offset:18432
	ds_read_b128 v[216:219], v249 offset:19456
	s_mov_b32 m0, s8
	s_nop 0
	global_load_lds_dwordx4 v208, s[12:13]
	s_add_i32 m0, s8, 0x2000
	s_nop 0
	global_load_lds_dwordx4 v204, s[12:13]
	s_barrier
	s_waitcnt lgkmcnt(0)
	s_setprio 1
	s_waitcnt lgkmcnt(0)
	v_mfma_f32_16x16x32_bf16 v[126:129], v[178:181], v[138:141], v[126:129]
	v_mfma_f32_16x16x32_bf16 v[114:117], v[186:189], v[138:141], v[114:117]
	v_mfma_f32_16x16x32_bf16 v[102:105], v[178:181], v[154:157], v[102:105]
	v_mfma_f32_16x16x32_bf16 v[98:101], v[186:189], v[154:157], v[98:101]
	v_mfma_f32_16x16x32_bf16 v[86:89], v[178:181], v[162:165], v[86:89]
	v_mfma_f32_16x16x32_bf16 v[82:85], v[186:189], v[162:165], v[82:85]
	v_mfma_f32_16x16x32_bf16 v[70:73], v[178:181], v[170:173], v[70:73]
	v_mfma_f32_16x16x32_bf16 v[66:69], v[186:189], v[170:173], v[66:69]
	v_mfma_f32_16x16x32_bf16 v[126:129], v[182:185], v[146:149], v[126:129]
	v_mfma_f32_16x16x32_bf16 v[114:117], v[216:219], v[146:149], v[114:117]
	v_mfma_f32_16x16x32_bf16 v[102:105], v[182:185], v[158:161], v[102:105]
	v_mfma_f32_16x16x32_bf16 v[98:101], v[216:219], v[158:161], v[98:101]
	v_mfma_f32_16x16x32_bf16 v[86:89], v[182:185], v[166:169], v[86:89]
	v_mfma_f32_16x16x32_bf16 v[82:85], v[216:219], v[166:169], v[82:85]
	v_mfma_f32_16x16x32_bf16 v[70:73], v[182:185], v[174:177], v[70:73]
	v_mfma_f32_16x16x32_bf16 v[66:69], v[216:219], v[174:177], v[66:69]
	s_setprio 0
	s_mov_b32 m0, s19
	s_add_u32 s98, s14, 0x80
	s_addc_u32 s99, s15, 0
	s_barrier
	ds_read_b128 v[138:141], v220 offset:16384
	ds_read_b128 v[146:149], v220 offset:17408
	ds_read_b128 v[154:157], v220 offset:18432
	ds_read_b128 v[158:161], v220 offset:19456
	ds_read_b128 v[162:165], v220 offset:20480
	ds_read_b128 v[166:169], v220 offset:21504
	ds_read_b128 v[170:173], v220 offset:22528
	ds_read_b128 v[174:177], v220 offset:23552
	global_load_lds_dwordx4 v210, s[14:15]
	s_mov_b32 m0, s20
	s_nop 0
	global_load_lds_dwordx4 v206, s[14:15]
	s_barrier
	s_waitcnt lgkmcnt(0)
	s_setprio 1
	s_waitcnt lgkmcnt(0)
	v_mfma_f32_16x16x32_bf16 v[62:65], v[118:121], v[138:141], v[62:65]
	v_mfma_f32_16x16x32_bf16 v[58:61], v[130:133], v[138:141], v[58:61]
	v_mfma_f32_16x16x32_bf16 v[46:49], v[118:121], v[154:157], v[46:49]
	v_mfma_f32_16x16x32_bf16 v[42:45], v[130:133], v[154:157], v[42:45]
	v_mfma_f32_16x16x32_bf16 v[30:33], v[118:121], v[162:165], v[30:33]
	v_mfma_f32_16x16x32_bf16 v[26:29], v[130:133], v[162:165], v[26:29]
	v_mfma_f32_16x16x32_bf16 v[14:17], v[118:121], v[170:173], v[14:17]
	v_mfma_f32_16x16x32_bf16 v[10:13], v[130:133], v[170:173], v[10:13]
	v_mfma_f32_16x16x32_bf16 v[62:65], v[122:125], v[146:149], v[62:65]
	v_mfma_f32_16x16x32_bf16 v[58:61], v[134:137], v[146:149], v[58:61]
	v_mfma_f32_16x16x32_bf16 v[46:49], v[122:125], v[158:161], v[46:49]
	v_mfma_f32_16x16x32_bf16 v[42:45], v[134:137], v[158:161], v[42:45]
	v_mfma_f32_16x16x32_bf16 v[30:33], v[122:125], v[166:169], v[30:33]
	v_mfma_f32_16x16x32_bf16 v[26:29], v[134:137], v[166:169], v[26:29]
	v_mfma_f32_16x16x32_bf16 v[14:17], v[122:125], v[174:177], v[14:17]
	v_mfma_f32_16x16x32_bf16 v[10:13], v[134:137], v[174:177], v[10:13]
	s_setprio 0
	s_barrier
	s_add_u32 s8, s12, 0xb0000
	s_addc_u32 s9, s13, 0
	s_add_i32 s37, s44, s18
	s_mov_b32 m0, s37
	s_nop 0
	global_load_lds_dwordx4 v208, s[8:9]
	s_add_i32 m0, s37, 0x2000
	s_nop 0
	global_load_lds_dwordx4 v204, s[8:9]
	s_waitcnt vmcnt(6)
	s_barrier
	s_setprio 1
	v_mfma_f32_16x16x32_bf16 v[54:57], v[178:181], v[138:141], v[54:57]
	v_mfma_f32_16x16x32_bf16 v[50:53], v[186:189], v[138:141], v[50:53]
	v_mfma_f32_16x16x32_bf16 v[38:41], v[178:181], v[154:157], v[38:41]
	v_mfma_f32_16x16x32_bf16 v[34:37], v[186:189], v[154:157], v[34:37]
	v_mfma_f32_16x16x32_bf16 v[22:25], v[178:181], v[162:165], v[22:25]
	v_mfma_f32_16x16x32_bf16 v[18:21], v[186:189], v[162:165], v[18:21]
	v_mfma_f32_16x16x32_bf16 v[6:9], v[178:181], v[170:173], v[6:9]
	v_mfma_f32_16x16x32_bf16 v[2:5], v[186:189], v[170:173], v[2:5]
	v_mfma_f32_16x16x32_bf16 v[54:57], v[182:185], v[146:149], v[54:57]
	v_mfma_f32_16x16x32_bf16 v[50:53], v[216:219], v[146:149], v[50:53]
	v_mfma_f32_16x16x32_bf16 v[38:41], v[182:185], v[158:161], v[38:41]
	v_mfma_f32_16x16x32_bf16 v[34:37], v[216:219], v[158:161], v[34:37]
	v_mfma_f32_16x16x32_bf16 v[22:25], v[182:185], v[166:169], v[22:25]
	v_mfma_f32_16x16x32_bf16 v[18:21], v[216:219], v[166:169], v[18:21]
	v_mfma_f32_16x16x32_bf16 v[6:9], v[182:185], v[174:177], v[6:9]
	v_mfma_f32_16x16x32_bf16 v[2:5], v[216:219], v[174:177], v[2:5]
	s_setprio 0
	s_add_i32 s37, 0, 0x18000
	s_barrier
	ds_read_b128 v[118:121], v249 offset:32768
	ds_read_b128 v[122:125], v249 offset:33792
	ds_read_b128 v[130:133], v249 offset:34816
	ds_read_b128 v[134:137], v249 offset:35840
	s_add_u32 s8, s14, 0xb0000
	s_addc_u32 s9, s15, 0
	s_mov_b32 m0, s21
	ds_read_b128 v[138:141], v220 offset:32768
	ds_read_b128 v[146:149], v220 offset:33792
	ds_read_b128 v[154:157], v220 offset:34816
	ds_read_b128 v[158:161], v220 offset:35840
	ds_read_b128 v[162:165], v220 offset:36864
	ds_read_b128 v[166:169], v220 offset:37888
	ds_read_b128 v[170:173], v220 offset:38912
	ds_read_b128 v[174:177], v220 offset:39936
	global_load_lds_dwordx4 v210, s[8:9]
	s_mov_b32 m0, s22
	s_nop 0
	global_load_lds_dwordx4 v206, s[8:9]
	s_waitcnt lgkmcnt(8)
	s_barrier
	s_waitcnt lgkmcnt(0)
	s_setprio 1
	s_waitcnt lgkmcnt(0)
	v_mfma_f32_16x16x32_bf16 v[150:153], v[118:121], v[138:141], v[150:153]
	v_mfma_f32_16x16x32_bf16 v[142:145], v[130:133], v[138:141], v[142:145]
	v_mfma_f32_16x16x32_bf16 v[110:113], v[118:121], v[154:157], v[110:113]
	v_mfma_f32_16x16x32_bf16 v[106:109], v[130:133], v[154:157], v[106:109]
	v_mfma_f32_16x16x32_bf16 v[94:97], v[118:121], v[162:165], v[94:97]
	v_mfma_f32_16x16x32_bf16 v[90:93], v[130:133], v[162:165], v[90:93]
	v_mfma_f32_16x16x32_bf16 v[78:81], v[118:121], v[170:173], v[78:81]
	v_mfma_f32_16x16x32_bf16 v[74:77], v[130:133], v[170:173], v[74:77]
	v_mfma_f32_16x16x32_bf16 v[150:153], v[122:125], v[146:149], v[150:153]
	v_mfma_f32_16x16x32_bf16 v[142:145], v[134:137], v[146:149], v[142:145]
	v_mfma_f32_16x16x32_bf16 v[110:113], v[122:125], v[158:161], v[110:113]
	v_mfma_f32_16x16x32_bf16 v[106:109], v[134:137], v[158:161], v[106:109]
	v_mfma_f32_16x16x32_bf16 v[94:97], v[122:125], v[166:169], v[94:97]
	v_mfma_f32_16x16x32_bf16 v[90:93], v[134:137], v[166:169], v[90:93]
	v_mfma_f32_16x16x32_bf16 v[78:81], v[122:125], v[174:177], v[78:81]
	v_mfma_f32_16x16x32_bf16 v[74:77], v[134:137], v[174:177], v[74:77]
	s_setprio 0
	s_barrier
	s_add_i32 s14, 0, 0x1c000
	s_add_i32 s8, s37, s18
	s_add_u32 vcc_lo, s12, 0x80
	s_addc_u32 vcc_hi, s13, 0
	s_mov_b32 m0, s8
	ds_read_b128 v[178:181], v249 offset:49152
	ds_read_b128 v[182:185], v249 offset:50176
	ds_read_b128 v[186:189], v249 offset:51200
	ds_read_b128 v[216:219], v249 offset:52224
	global_load_lds_dwordx4 v208, vcc
	s_add_i32 m0, s8, 0x2000
	s_nop 0
	global_load_lds_dwordx4 v204, vcc
	s_barrier
	s_waitcnt lgkmcnt(0)
	s_setprio 1
	s_waitcnt lgkmcnt(0)
	v_mfma_f32_16x16x32_bf16 v[126:129], v[178:181], v[138:141], v[126:129]
	v_mfma_f32_16x16x32_bf16 v[114:117], v[186:189], v[138:141], v[114:117]
	v_mfma_f32_16x16x32_bf16 v[102:105], v[178:181], v[154:157], v[102:105]
	v_mfma_f32_16x16x32_bf16 v[98:101], v[186:189], v[154:157], v[98:101]
	v_mfma_f32_16x16x32_bf16 v[86:89], v[178:181], v[162:165], v[86:89]
	v_mfma_f32_16x16x32_bf16 v[82:85], v[186:189], v[162:165], v[82:85]
	v_mfma_f32_16x16x32_bf16 v[70:73], v[178:181], v[170:173], v[70:73]
	v_mfma_f32_16x16x32_bf16 v[66:69], v[186:189], v[170:173], v[66:69]
	v_mfma_f32_16x16x32_bf16 v[126:129], v[182:185], v[146:149], v[126:129]
	v_mfma_f32_16x16x32_bf16 v[114:117], v[216:219], v[146:149], v[114:117]
	v_mfma_f32_16x16x32_bf16 v[102:105], v[182:185], v[158:161], v[102:105]
	v_mfma_f32_16x16x32_bf16 v[98:101], v[216:219], v[158:161], v[98:101]
	v_mfma_f32_16x16x32_bf16 v[86:89], v[182:185], v[166:169], v[86:89]
	v_mfma_f32_16x16x32_bf16 v[82:85], v[216:219], v[166:169], v[82:85]
	v_mfma_f32_16x16x32_bf16 v[70:73], v[182:185], v[174:177], v[70:73]
	v_mfma_f32_16x16x32_bf16 v[66:69], v[216:219], v[174:177], v[66:69]
	s_setprio 0
	s_mov_b32 m0, s24
	s_barrier
	ds_read_b128 v[138:141], v220 offset:49152
	ds_read_b128 v[146:149], v220 offset:50176
	ds_read_b128 v[154:157], v220 offset:51200
	ds_read_b128 v[158:161], v220 offset:52224
	ds_read_b128 v[162:165], v220 offset:53248
	ds_read_b128 v[166:169], v220 offset:54272
	ds_read_b128 v[170:173], v220 offset:55296
	ds_read_b128 v[174:177], v220 offset:56320
	global_load_lds_dwordx4 v210, s[98:99]
	s_mov_b32 m0, s25
	s_nop 0
	global_load_lds_dwordx4 v206, s[98:99]
	s_barrier
	s_waitcnt lgkmcnt(0)
	s_setprio 1
	s_waitcnt lgkmcnt(0)
	v_mfma_f32_16x16x32_bf16 v[62:65], v[118:121], v[138:141], v[62:65]
	v_mfma_f32_16x16x32_bf16 v[58:61], v[130:133], v[138:141], v[58:61]
	v_mfma_f32_16x16x32_bf16 v[46:49], v[118:121], v[154:157], v[46:49]
	v_mfma_f32_16x16x32_bf16 v[42:45], v[130:133], v[154:157], v[42:45]
	v_mfma_f32_16x16x32_bf16 v[30:33], v[118:121], v[162:165], v[30:33]
	v_mfma_f32_16x16x32_bf16 v[26:29], v[130:133], v[162:165], v[26:29]
	v_mfma_f32_16x16x32_bf16 v[14:17], v[118:121], v[170:173], v[14:17]
	v_mfma_f32_16x16x32_bf16 v[10:13], v[130:133], v[170:173], v[10:13]
	v_mfma_f32_16x16x32_bf16 v[62:65], v[122:125], v[146:149], v[62:65]
	v_mfma_f32_16x16x32_bf16 v[58:61], v[134:137], v[146:149], v[58:61]
	v_mfma_f32_16x16x32_bf16 v[46:49], v[122:125], v[158:161], v[46:49]
	v_mfma_f32_16x16x32_bf16 v[42:45], v[134:137], v[158:161], v[42:45]
	v_mfma_f32_16x16x32_bf16 v[30:33], v[122:125], v[166:169], v[30:33]
	v_mfma_f32_16x16x32_bf16 v[26:29], v[134:137], v[166:169], v[26:29]
	v_mfma_f32_16x16x32_bf16 v[14:17], v[122:125], v[174:177], v[14:17]
	v_mfma_f32_16x16x32_bf16 v[10:13], v[134:137], v[174:177], v[10:13]
	s_setprio 0
	s_barrier
	s_add_u32 s8, s12, 0xb0080
	s_addc_u32 s9, s13, 0
	s_add_i32 s12, s14, s18
	s_mov_b32 m0, s12
	s_nop 0
	global_load_lds_dwordx4 v208, s[8:9]
	s_add_i32 m0, s12, 0x2000
	s_nop 0
	global_load_lds_dwordx4 v204, s[8:9]
	s_waitcnt vmcnt(6)
	s_barrier
	s_setprio 1
	v_mfma_f32_16x16x32_bf16 v[54:57], v[178:181], v[138:141], v[54:57]
	v_mfma_f32_16x16x32_bf16 v[50:53], v[186:189], v[138:141], v[50:53]
	v_mfma_f32_16x16x32_bf16 v[38:41], v[178:181], v[154:157], v[38:41]
	v_mfma_f32_16x16x32_bf16 v[34:37], v[186:189], v[154:157], v[34:37]
	v_mfma_f32_16x16x32_bf16 v[22:25], v[178:181], v[162:165], v[22:25]
	v_mfma_f32_16x16x32_bf16 v[18:21], v[186:189], v[162:165], v[18:21]
	v_mfma_f32_16x16x32_bf16 v[6:9], v[178:181], v[170:173], v[6:9]
	v_mfma_f32_16x16x32_bf16 v[2:5], v[186:189], v[170:173], v[2:5]
	v_mfma_f32_16x16x32_bf16 v[54:57], v[182:185], v[146:149], v[54:57]
	v_mfma_f32_16x16x32_bf16 v[50:53], v[216:219], v[146:149], v[50:53]
	v_mfma_f32_16x16x32_bf16 v[38:41], v[182:185], v[158:161], v[38:41]
	v_mfma_f32_16x16x32_bf16 v[34:37], v[216:219], v[158:161], v[34:37]
	v_mfma_f32_16x16x32_bf16 v[22:25], v[182:185], v[166:169], v[22:25]
	v_mfma_f32_16x16x32_bf16 v[18:21], v[216:219], v[166:169], v[18:21]
	v_mfma_f32_16x16x32_bf16 v[6:9], v[182:185], v[174:177], v[6:9]
	v_mfma_f32_16x16x32_bf16 v[2:5], v[216:219], v[174:177], v[2:5]
	s_setprio 0
	s_add_i32 s36, s36, 2
	s_add_u32 s34, s34, 0x100
	s_addc_u32 s35, s35, 0
	s_cmp_gt_u32 s36, 41
	s_mov_b64 s[8:9], s[10:11]
	s_barrier
	s_cbranch_scc0 .LBB0_1103
	v_lshl_add_u32 v216, s31, 8, v199
	v_ashrrev_i32_e32 v217, 31, v216
	v_readlane_b32 s8, v252, 51
	v_lshlrev_b64 v[118:119], 11, v[216:217]
	v_readlane_b32 s9, v252, 52
	s_nop 1
	v_lshl_add_u64 v[118:119], s[8:9], 0, v[118:119]
	s_lshl_b32 s8, s30, 8
	s_ashr_i32 s9, s8, 31
	v_lshl_add_u64 v[118:119], s[8:9], 1, v[118:119]
	v_lshl_add_u64 v[118:119], v[118:119], 0, s[96:97]
	v_lshl_add_u64 v[218:219], v[118:119], 0, v[190:191]
	global_load_dwordx4 v[222:225], v[218:219], off
	global_load_dwordx4 v[186:189], v[218:219], off offset:256
	s_mov_b32 s8, 0x8000
	v_add_co_u32_e32 v118, vcc, s8, v218
	s_mov_b32 s8, 0x10000
	s_nop 0
	v_addc_co_u32_e32 v119, vcc, 0, v219, vcc
	global_load_dwordx4 v[182:185], v[118:119], off
	global_load_dwordx4 v[178:181], v[118:119], off offset:256
	v_add_co_u32_e32 v118, vcc, s8, v218
	s_mov_b32 s8, 0x18000
	s_nop 0
	v_addc_co_u32_e32 v119, vcc, 0, v219, vcc
	global_load_dwordx4 v[174:177], v[118:119], off
	global_load_dwordx4 v[170:173], v[118:119], off offset:256
	v_add_co_u32_e32 v118, vcc, s8, v218
	s_lshl_b32 s8, s30, 2
	s_nop 0
	v_addc_co_u32_e32 v119, vcc, 0, v219, vcc
	global_load_dwordx4 v[166:169], v[118:119], off
	global_load_dwordx4 v[162:165], v[118:119], off offset:256
	v_add_co_u32_e32 v118, vcc, s45, v218
	s_ashr_i32 s9, s8, 31
	s_nop 0
	v_addc_co_u32_e32 v119, vcc, 0, v219, vcc
	global_load_dwordx4 v[158:161], v[118:119], off
	global_load_dwordx4 v[154:157], v[118:119], off offset:256
	v_add_co_u32_e32 v118, vcc, s46, v218
	s_waitcnt vmcnt(0)
	v_lshlrev_b32_e32 v192, 16, v222
	v_addc_co_u32_e32 v119, vcc, 0, v219, vcc
	global_load_dwordx4 v[146:149], v[118:119], off
	global_load_dwordx4 v[138:141], v[118:119], off offset:256
	v_add_co_u32_e32 v118, vcc, s47, v218
	v_add_f32_e32 v150, v150, v192
	s_nop 0
	v_addc_co_u32_e32 v119, vcc, 0, v219, vcc
	global_load_dwordx4 v[134:137], v[118:119], off
	global_load_dwordx4 v[130:133], v[118:119], off offset:256
	v_add_co_u32_e32 v118, vcc, s48, v218
	v_and_b32_e32 v192, 0xffff0000, v222
	s_nop 0
	v_addc_co_u32_e32 v119, vcc, 0, v219, vcc
	global_load_dwordx4 v[122:125], v[118:119], off
	s_nop 0
	global_load_dwordx4 v[118:121], v[118:119], off offset:256
	v_add_f32_e32 v151, v151, v192
	v_lshlrev_b32_e32 v192, 16, v223
	v_mul_f32_e32 v195, v151, v151
	v_add_f32_e32 v152, v152, v192
	v_and_b32_e32 v192, 0xffff0000, v223
	v_fmac_f32_e32 v195, v150, v150
	v_add_f32_e32 v153, v153, v192
	v_lshlrev_b32_e32 v192, 16, v224
	v_fmac_f32_e32 v195, v152, v152
	v_add_f32_e32 v192, v142, v192
	v_and_b32_e32 v142, 0xffff0000, v224
	v_fmac_f32_e32 v195, v153, v153
	v_add_f32_e32 v193, v143, v142
	v_lshlrev_b32_e32 v142, 16, v225
	v_fmac_f32_e32 v195, v192, v192
	v_add_f32_e32 v194, v144, v142
	v_and_b32_e32 v142, 0xffff0000, v225
	v_fmac_f32_e32 v195, v193, v193
	v_add_f32_e32 v145, v145, v142
	v_fmac_f32_e32 v195, v194, v194
	v_cvt_pk_bf16_f32 v142, v150, v151
	v_fmac_f32_e32 v195, v145, v145
	v_cvt_pk_bf16_f32 v143, v152, v153
	v_cvt_pk_bf16_f32 v144, v192, v193
	v_cvt_pk_bf16_f32 v145, v194, v145
	global_store_dwordx4 v[218:219], v[142:145], off
	s_nop 1
	v_lshlrev_b32_e32 v142, 16, v186
	v_add_f32_e32 v126, v126, v142
	v_and_b32_e32 v142, 0xffff0000, v186
	v_add_f32_e32 v127, v127, v142
	v_lshlrev_b32_e32 v142, 16, v187
	v_fmac_f32_e32 v195, v126, v126
	v_add_f32_e32 v128, v128, v142
	v_and_b32_e32 v142, 0xffff0000, v187
	v_fmac_f32_e32 v195, v127, v127
	v_add_f32_e32 v129, v129, v142
	v_lshlrev_b32_e32 v142, 16, v188
	v_fmac_f32_e32 v195, v128, v128
	v_add_f32_e32 v142, v114, v142
	v_and_b32_e32 v114, 0xffff0000, v188
	v_fmac_f32_e32 v195, v129, v129
	v_add_f32_e32 v143, v115, v114
	v_lshlrev_b32_e32 v114, 16, v189
	v_fmac_f32_e32 v195, v142, v142
	v_add_f32_e32 v144, v116, v114
	v_and_b32_e32 v114, 0xffff0000, v189
	v_fmac_f32_e32 v195, v143, v143
	v_add_f32_e32 v117, v117, v114
	v_fmac_f32_e32 v195, v144, v144
	v_cvt_pk_bf16_f32 v115, v128, v129
	v_fmac_f32_e32 v195, v117, v117
	v_cvt_pk_bf16_f32 v114, v126, v127
	v_cvt_pk_bf16_f32 v116, v142, v143
	v_cvt_pk_bf16_f32 v117, v144, v117
	global_store_dwordx4 v[218:219], v[114:117], off offset:256
	s_nop 1
	v_and_b32_e32 v115, 64, v244
	v_xor_b32_e32 v114, 16, v244
	v_add_u32_e32 v115, 64, v115
	v_cmp_lt_i32_e32 vcc, v114, v115
	v_xor_b32_e32 v117, 32, v244
	s_nop 0
	v_cndmask_b32_e32 v114, v244, v114, vcc
	v_lshlrev_b32_e32 v114, 2, v114
	ds_bpermute_b32 v116, v114, v195
	v_cmp_lt_i32_e32 vcc, v117, v115
	s_waitcnt lgkmcnt(0)
	v_add_f32_e32 v116, v195, v116
	v_cndmask_b32_e32 v115, v244, v117, vcc
	v_lshlrev_b32_e32 v115, 2, v115
	ds_bpermute_b32 v117, v115, v116
	s_and_saveexec_b64 s[10:11], s[40:41]
	s_cbranch_execz .LBB0_1106
	v_readlane_b32 s12, v252, 53
	s_waitcnt lgkmcnt(0)
	v_add_f32_e32 v126, v116, v117
	v_lshlrev_b64 v[116:117], 6, v[216:217]
	v_readlane_b32 s13, v252, 54
	s_nop 1
	v_lshl_add_u64 v[116:117], s[12:13], 0, v[116:117]
	v_lshl_add_u64 v[116:117], s[8:9], 2, v[116:117]
	s_lshl_b32 s12, s23, 2
	s_mov_b32 s13, s97
	v_lshl_add_u64 v[116:117], v[116:117], 0, s[12:13]
	global_store_dword v[116:117], v126, off

.LBB0_1156:
	s_add_u32 s16, s14, 0xfffc0080
	s_addc_u32 s17, s15, -1
	s_add_i32 s41, 0, 0x10000
	v_add_u32_e32 v249, s41, v154
	ds_read_b128 v[146:149], v249
	ds_read_b128 v[150:153], v249 offset:1024
	ds_read_b128 v[164:167], v249 offset:2048
	ds_read_b128 v[168:171], v249 offset:3072
	s_cmp_eq_u32 s40, 12
	s_cselect_b32 s19, s5, s17
	s_cselect_b32 s18, s34, s16
	s_cselect_b32 s17, s3, s37
	s_cselect_b32 s16, s35, s36
	s_add_i32 m0, s9, 0xc000
	ds_read_b128 v[172:175], v163
	ds_read_b128 v[176:179], v163 offset:1024
	ds_read_b128 v[180:183], v163 offset:2048
	ds_read_b128 v[184:187], v163 offset:3072
	ds_read_b128 v[204:207], v163 offset:4096
	ds_read_b128 v[208:211], v163 offset:5120
	ds_read_b128 v[212:215], v163 offset:6144
	ds_read_b128 v[216:219], v163 offset:7168
	global_load_lds_dwordx4 v138, s[14:15]
	s_add_i32 m0, s9, 0xe000
	s_nop 0
	global_load_lds_dwordx4 v140, s[14:15]
	s_waitcnt lgkmcnt(8)
	s_barrier
	s_waitcnt lgkmcnt(0)
	s_setprio 1
	s_waitcnt lgkmcnt(0)
	v_mfma_f32_16x16x32_bf16 v[126:129], v[146:149], v[172:175], v[126:129]
	v_mfma_f32_16x16x32_bf16 v[122:125], v[164:167], v[172:175], v[122:125]
	v_mfma_f32_16x16x32_bf16 v[114:117], v[146:149], v[180:183], v[114:117]
	v_mfma_f32_16x16x32_bf16 v[106:109], v[164:167], v[180:183], v[106:109]
	v_mfma_f32_16x16x32_bf16 v[98:101], v[146:149], v[204:207], v[98:101]
	v_mfma_f32_16x16x32_bf16 v[90:93], v[164:167], v[204:207], v[90:93]
	v_mfma_f32_16x16x32_bf16 v[82:85], v[146:149], v[212:215], v[82:85]
	v_mfma_f32_16x16x32_bf16 v[74:77], v[164:167], v[212:215], v[74:77]
	v_mfma_f32_16x16x32_bf16 v[126:129], v[150:153], v[176:179], v[126:129]
	v_mfma_f32_16x16x32_bf16 v[122:125], v[168:171], v[176:179], v[122:125]
	v_mfma_f32_16x16x32_bf16 v[114:117], v[150:153], v[184:187], v[114:117]
	v_mfma_f32_16x16x32_bf16 v[106:109], v[168:171], v[184:187], v[106:109]
	v_mfma_f32_16x16x32_bf16 v[98:101], v[150:153], v[208:211], v[98:101]
	v_mfma_f32_16x16x32_bf16 v[90:93], v[168:171], v[208:211], v[90:93]
	v_mfma_f32_16x16x32_bf16 v[82:85], v[150:153], v[216:219], v[82:85]
	v_mfma_f32_16x16x32_bf16 v[74:77], v[168:171], v[216:219], v[74:77]
	s_setprio 0
	s_barrier
	s_add_i32 s44, 0, 0x14000
	s_add_i32 s41, s41, s25
	s_mov_b32 m0, s41
	ds_read_b128 v[220:223], v249 offset:16384
	ds_read_b128 v[224:227], v249 offset:17408
	ds_read_b128 v[228:231], v249 offset:18432
	ds_read_b128 v[232:235], v249 offset:19456
	global_load_lds_dwordx4 v132, s[16:17]
	s_add_i32 m0, s41, 0x2000
	s_nop 0
	global_load_lds_dwordx4 v136, s[16:17]
	s_barrier
	s_waitcnt lgkmcnt(0)
	s_setprio 1
	s_waitcnt lgkmcnt(0)
	v_mfma_f32_16x16x32_bf16 v[118:121], v[220:223], v[172:175], v[118:121]
	v_mfma_f32_16x16x32_bf16 v[110:113], v[228:231], v[172:175], v[110:113]
	v_mfma_f32_16x16x32_bf16 v[102:105], v[220:223], v[180:183], v[102:105]
	v_mfma_f32_16x16x32_bf16 v[94:97], v[228:231], v[180:183], v[94:97]
	v_mfma_f32_16x16x32_bf16 v[86:89], v[220:223], v[204:207], v[86:89]
	v_mfma_f32_16x16x32_bf16 v[78:81], v[228:231], v[204:207], v[78:81]
	v_mfma_f32_16x16x32_bf16 v[70:73], v[220:223], v[212:215], v[70:73]
	v_mfma_f32_16x16x32_bf16 v[66:69], v[228:231], v[212:215], v[66:69]
	v_mfma_f32_16x16x32_bf16 v[118:121], v[224:227], v[176:179], v[118:121]
	v_mfma_f32_16x16x32_bf16 v[110:113], v[232:235], v[176:179], v[110:113]
	v_mfma_f32_16x16x32_bf16 v[102:105], v[224:227], v[184:187], v[102:105]
	v_mfma_f32_16x16x32_bf16 v[94:97], v[232:235], v[184:187], v[94:97]
	v_mfma_f32_16x16x32_bf16 v[86:89], v[224:227], v[208:211], v[86:89]
	v_mfma_f32_16x16x32_bf16 v[78:81], v[232:235], v[208:211], v[78:81]
	v_mfma_f32_16x16x32_bf16 v[70:73], v[224:227], v[216:219], v[70:73]
	v_mfma_f32_16x16x32_bf16 v[66:69], v[232:235], v[216:219], v[66:69]
	s_setprio 0
	s_mov_b32 m0, s9
	s_add_u32 s98, s18, 0x80
	s_addc_u32 s99, s19, 0
	s_barrier
	ds_read_b128 v[172:175], v163 offset:16384
	ds_read_b128 v[176:179], v163 offset:17408
	ds_read_b128 v[180:183], v163 offset:18432
	ds_read_b128 v[184:187], v163 offset:19456
	ds_read_b128 v[204:207], v163 offset:20480
	ds_read_b128 v[208:211], v163 offset:21504
	ds_read_b128 v[212:215], v163 offset:22528
	ds_read_b128 v[216:219], v163 offset:23552
	global_load_lds_dwordx4 v130, s[18:19]
	s_mov_b32 m0, s26
	s_nop 0
	global_load_lds_dwordx4 v134, s[18:19]
	s_barrier
	s_waitcnt lgkmcnt(0)
	s_setprio 1
	s_waitcnt lgkmcnt(0)
	v_mfma_f32_16x16x32_bf16 v[62:65], v[146:149], v[172:175], v[62:65]
	v_mfma_f32_16x16x32_bf16 v[58:61], v[164:167], v[172:175], v[58:61]
	v_mfma_f32_16x16x32_bf16 v[50:53], v[146:149], v[180:183], v[50:53]
	v_mfma_f32_16x16x32_bf16 v[42:45], v[164:167], v[180:183], v[42:45]
	v_mfma_f32_16x16x32_bf16 v[34:37], v[146:149], v[204:207], v[34:37]
	v_mfma_f32_16x16x32_bf16 v[26:29], v[164:167], v[204:207], v[26:29]
	v_mfma_f32_16x16x32_bf16 v[18:21], v[146:149], v[212:215], v[18:21]
	v_mfma_f32_16x16x32_bf16 v[10:13], v[164:167], v[212:215], v[10:13]
	v_mfma_f32_16x16x32_bf16 v[62:65], v[150:153], v[176:179], v[62:65]
	v_mfma_f32_16x16x32_bf16 v[58:61], v[168:171], v[176:179], v[58:61]
	v_mfma_f32_16x16x32_bf16 v[50:53], v[150:153], v[184:187], v[50:53]
	v_mfma_f32_16x16x32_bf16 v[42:45], v[168:171], v[184:187], v[42:45]
	v_mfma_f32_16x16x32_bf16 v[34:37], v[150:153], v[208:211], v[34:37]
	v_mfma_f32_16x16x32_bf16 v[26:29], v[168:171], v[208:211], v[26:29]
	v_mfma_f32_16x16x32_bf16 v[18:21], v[150:153], v[216:219], v[18:21]
	v_mfma_f32_16x16x32_bf16 v[10:13], v[168:171], v[216:219], v[10:13]
	s_setprio 0
	s_barrier
	s_add_u32 s42, s16, 0x40000
	s_addc_u32 s43, s17, 0
	s_add_i32 s41, s44, s25
	s_mov_b32 m0, s41
	s_nop 0
	global_load_lds_dwordx4 v132, s[42:43]
	s_add_i32 m0, s41, 0x2000
	s_nop 0
	global_load_lds_dwordx4 v136, s[42:43]
	s_waitcnt vmcnt(6)
	s_barrier
	s_setprio 1
	v_mfma_f32_16x16x32_bf16 v[54:57], v[220:223], v[172:175], v[54:57]
	v_mfma_f32_16x16x32_bf16 v[46:49], v[228:231], v[172:175], v[46:49]
	v_mfma_f32_16x16x32_bf16 v[38:41], v[220:223], v[180:183], v[38:41]
	v_mfma_f32_16x16x32_bf16 v[30:33], v[228:231], v[180:183], v[30:33]
	v_mfma_f32_16x16x32_bf16 v[22:25], v[220:223], v[204:207], v[22:25]
	v_mfma_f32_16x16x32_bf16 v[14:17], v[228:231], v[204:207], v[14:17]
	v_mfma_f32_16x16x32_bf16 v[6:9], v[220:223], v[212:215], v[6:9]
	v_mfma_f32_16x16x32_bf16 v[2:5], v[228:231], v[212:215], v[2:5]
	v_mfma_f32_16x16x32_bf16 v[54:57], v[224:227], v[176:179], v[54:57]
	v_mfma_f32_16x16x32_bf16 v[46:49], v[232:235], v[176:179], v[46:49]
	v_mfma_f32_16x16x32_bf16 v[38:41], v[224:227], v[184:187], v[38:41]
	v_mfma_f32_16x16x32_bf16 v[30:33], v[232:235], v[184:187], v[30:33]
	v_mfma_f32_16x16x32_bf16 v[22:25], v[224:227], v[208:211], v[22:25]
	v_mfma_f32_16x16x32_bf16 v[14:17], v[232:235], v[208:211], v[14:17]
	v_mfma_f32_16x16x32_bf16 v[6:9], v[224:227], v[216:219], v[6:9]
	v_mfma_f32_16x16x32_bf16 v[2:5], v[232:235], v[216:219], v[2:5]
	s_setprio 0
	s_add_i32 s41, 0, 0x18000
	s_barrier
	ds_read_b128 v[146:149], v249 offset:32768
	ds_read_b128 v[150:153], v249 offset:33792
	ds_read_b128 v[164:167], v249 offset:34816
	ds_read_b128 v[168:171], v249 offset:35840
	s_add_u32 s18, s18, 0x40000
	s_addc_u32 s19, s19, 0
	s_mov_b32 m0, s27
	ds_read_b128 v[172:175], v163 offset:32768
	ds_read_b128 v[176:179], v163 offset:33792
	ds_read_b128 v[180:183], v163 offset:34816
	ds_read_b128 v[184:187], v163 offset:35840
	ds_read_b128 v[204:207], v163 offset:36864
	ds_read_b128 v[208:211], v163 offset:37888
	ds_read_b128 v[212:215], v163 offset:38912
	ds_read_b128 v[216:219], v163 offset:39936
	global_load_lds_dwordx4 v130, s[18:19]
	s_mov_b32 m0, s28
	s_nop 0
	global_load_lds_dwordx4 v134, s[18:19]
	s_waitcnt lgkmcnt(8)
	s_barrier
	s_waitcnt lgkmcnt(0)
	s_setprio 1
	s_waitcnt lgkmcnt(0)
	v_mfma_f32_16x16x32_bf16 v[126:129], v[146:149], v[172:175], v[126:129]
	v_mfma_f32_16x16x32_bf16 v[122:125], v[164:167], v[172:175], v[122:125]
	v_mfma_f32_16x16x32_bf16 v[114:117], v[146:149], v[180:183], v[114:117]
	v_mfma_f32_16x16x32_bf16 v[106:109], v[164:167], v[180:183], v[106:109]
	v_mfma_f32_16x16x32_bf16 v[98:101], v[146:149], v[204:207], v[98:101]
	v_mfma_f32_16x16x32_bf16 v[90:93], v[164:167], v[204:207], v[90:93]
	v_mfma_f32_16x16x32_bf16 v[82:85], v[146:149], v[212:215], v[82:85]
	v_mfma_f32_16x16x32_bf16 v[74:77], v[164:167], v[212:215], v[74:77]
	v_mfma_f32_16x16x32_bf16 v[126:129], v[150:153], v[176:179], v[126:129]
	v_mfma_f32_16x16x32_bf16 v[122:125], v[168:171], v[176:179], v[122:125]
	v_mfma_f32_16x16x32_bf16 v[114:117], v[150:153], v[184:187], v[114:117]
	v_mfma_f32_16x16x32_bf16 v[106:109], v[168:171], v[184:187], v[106:109]
	v_mfma_f32_16x16x32_bf16 v[98:101], v[150:153], v[208:211], v[98:101]
	v_mfma_f32_16x16x32_bf16 v[90:93], v[168:171], v[208:211], v[90:93]
	v_mfma_f32_16x16x32_bf16 v[82:85], v[150:153], v[216:219], v[82:85]
	v_mfma_f32_16x16x32_bf16 v[74:77], v[168:171], v[216:219], v[74:77]
	s_setprio 0
	s_barrier
	s_add_i32 s18, 0, 0x1c000
	s_add_i32 s19, s41, s25
	s_add_u32 vcc_lo, s16, 0x80
	s_addc_u32 vcc_hi, s17, 0
	s_mov_b32 m0, s19
	ds_read_b128 v[220:223], v249 offset:49152
	ds_read_b128 v[224:227], v249 offset:50176
	ds_read_b128 v[228:231], v249 offset:51200
	ds_read_b128 v[232:235], v249 offset:52224
	global_load_lds_dwordx4 v132, vcc
	s_add_i32 m0, s19, 0x2000
	s_nop 0
	global_load_lds_dwordx4 v136, vcc
	s_barrier
	s_waitcnt lgkmcnt(0)
	s_setprio 1
	s_waitcnt lgkmcnt(0)
	v_mfma_f32_16x16x32_bf16 v[118:121], v[220:223], v[172:175], v[118:121]
	v_mfma_f32_16x16x32_bf16 v[110:113], v[228:231], v[172:175], v[110:113]
	v_mfma_f32_16x16x32_bf16 v[102:105], v[220:223], v[180:183], v[102:105]
	v_mfma_f32_16x16x32_bf16 v[94:97], v[228:231], v[180:183], v[94:97]
	v_mfma_f32_16x16x32_bf16 v[86:89], v[220:223], v[204:207], v[86:89]
	v_mfma_f32_16x16x32_bf16 v[78:81], v[228:231], v[204:207], v[78:81]
	v_mfma_f32_16x16x32_bf16 v[70:73], v[220:223], v[212:215], v[70:73]
	v_mfma_f32_16x16x32_bf16 v[66:69], v[228:231], v[212:215], v[66:69]
	v_mfma_f32_16x16x32_bf16 v[118:121], v[224:227], v[176:179], v[118:121]
	v_mfma_f32_16x16x32_bf16 v[110:113], v[232:235], v[176:179], v[110:113]
	v_mfma_f32_16x16x32_bf16 v[102:105], v[224:227], v[184:187], v[102:105]
	v_mfma_f32_16x16x32_bf16 v[94:97], v[232:235], v[184:187], v[94:97]
	v_mfma_f32_16x16x32_bf16 v[86:89], v[224:227], v[208:211], v[86:89]
	v_mfma_f32_16x16x32_bf16 v[78:81], v[232:235], v[208:211], v[78:81]
	v_mfma_f32_16x16x32_bf16 v[70:73], v[224:227], v[216:219], v[70:73]
	v_mfma_f32_16x16x32_bf16 v[66:69], v[232:235], v[216:219], v[66:69]
	s_setprio 0
	s_mov_b32 m0, s29
	s_barrier
	ds_read_b128 v[172:175], v163 offset:49152
	ds_read_b128 v[176:179], v163 offset:50176
	ds_read_b128 v[180:183], v163 offset:51200
	ds_read_b128 v[184:187], v163 offset:52224
	ds_read_b128 v[204:207], v163 offset:53248
	ds_read_b128 v[208:211], v163 offset:54272
	ds_read_b128 v[212:215], v163 offset:55296
	ds_read_b128 v[216:219], v163 offset:56320
	global_load_lds_dwordx4 v130, s[98:99]
	s_mov_b32 m0, s30
	s_nop 0
	global_load_lds_dwordx4 v134, s[98:99]
	s_barrier
	s_waitcnt lgkmcnt(0)
	s_setprio 1
	s_waitcnt lgkmcnt(0)
	v_mfma_f32_16x16x32_bf16 v[62:65], v[146:149], v[172:175], v[62:65]
	v_mfma_f32_16x16x32_bf16 v[58:61], v[164:167], v[172:175], v[58:61]
	v_mfma_f32_16x16x32_bf16 v[50:53], v[146:149], v[180:183], v[50:53]
	v_mfma_f32_16x16x32_bf16 v[42:45], v[164:167], v[180:183], v[42:45]
	v_mfma_f32_16x16x32_bf16 v[34:37], v[146:149], v[204:207], v[34:37]
	v_mfma_f32_16x16x32_bf16 v[26:29], v[164:167], v[204:207], v[26:29]
	v_mfma_f32_16x16x32_bf16 v[18:21], v[146:149], v[212:215], v[18:21]
	v_mfma_f32_16x16x32_bf16 v[10:13], v[164:167], v[212:215], v[10:13]
	v_mfma_f32_16x16x32_bf16 v[62:65], v[150:153], v[176:179], v[62:65]
	v_mfma_f32_16x16x32_bf16 v[58:61], v[168:171], v[176:179], v[58:61]
	v_mfma_f32_16x16x32_bf16 v[50:53], v[150:153], v[184:187], v[50:53]
	v_mfma_f32_16x16x32_bf16 v[42:45], v[168:171], v[184:187], v[42:45]
	v_mfma_f32_16x16x32_bf16 v[34:37], v[150:153], v[208:211], v[34:37]
	v_mfma_f32_16x16x32_bf16 v[26:29], v[168:171], v[208:211], v[26:29]
	v_mfma_f32_16x16x32_bf16 v[18:21], v[150:153], v[216:219], v[18:21]
	v_mfma_f32_16x16x32_bf16 v[10:13], v[168:171], v[216:219], v[10:13]
	s_setprio 0
	s_barrier
	s_add_u32 s16, s16, 0x40080
	s_addc_u32 s17, s17, 0
	s_add_i32 s18, s18, s25
	s_mov_b32 m0, s18
	s_nop 0
	global_load_lds_dwordx4 v132, s[16:17]
	s_add_i32 m0, s18, 0x2000
	s_nop 0
	global_load_lds_dwordx4 v136, s[16:17]
	s_waitcnt vmcnt(6)
	s_barrier
	s_setprio 1
	v_mfma_f32_16x16x32_bf16 v[54:57], v[220:223], v[172:175], v[54:57]
	v_mfma_f32_16x16x32_bf16 v[46:49], v[228:231], v[172:175], v[46:49]
	v_mfma_f32_16x16x32_bf16 v[38:41], v[220:223], v[180:183], v[38:41]
	v_mfma_f32_16x16x32_bf16 v[30:33], v[228:231], v[180:183], v[30:33]
	v_mfma_f32_16x16x32_bf16 v[22:25], v[220:223], v[204:207], v[22:25]
	v_mfma_f32_16x16x32_bf16 v[14:17], v[228:231], v[204:207], v[14:17]
	v_mfma_f32_16x16x32_bf16 v[6:9], v[220:223], v[212:215], v[6:9]
	v_mfma_f32_16x16x32_bf16 v[2:5], v[228:231], v[212:215], v[2:5]
	v_mfma_f32_16x16x32_bf16 v[54:57], v[224:227], v[176:179], v[54:57]
	v_mfma_f32_16x16x32_bf16 v[46:49], v[232:235], v[176:179], v[46:49]
	v_mfma_f32_16x16x32_bf16 v[38:41], v[224:227], v[184:187], v[38:41]
	v_mfma_f32_16x16x32_bf16 v[30:33], v[232:235], v[184:187], v[30:33]
	v_mfma_f32_16x16x32_bf16 v[22:25], v[224:227], v[208:211], v[22:25]
	v_mfma_f32_16x16x32_bf16 v[14:17], v[232:235], v[208:211], v[14:17]
	v_mfma_f32_16x16x32_bf16 v[6:9], v[224:227], v[216:219], v[6:9]
	v_mfma_f32_16x16x32_bf16 v[2:5], v[232:235], v[216:219], v[2:5]
	s_setprio 0
	s_add_i32 s40, s40, 2
	s_add_u32 s14, s14, 0x100
	s_addc_u32 s15, s15, 0
	s_add_u32 s36, s36, 0x100
	s_addc_u32 s37, s37, 0
	s_cmp_gt_u32 s40, 13
	s_barrier
	s_cbranch_scc0 .LBB0_1156
	s_mov_b64 s[14:15], -1
	s_cmp_gt_i32 s6, 5
	v_lshl_add_u32 v143, s7, 8, v145
	s_cbranch_scc0 .LBB0_1175
	v_lshl_add_u32 v144, v143, 2, 0
	v_add_u32_e32 v164, 0x20040, v144
	ds_read_b32 v144, v164
	s_cmp_gt_u32 s6, 7
	s_cselect_b64 s[14:15], -1, 0
	s_cmp_lt_u32 s6, 8
	s_waitcnt lgkmcnt(0)
	v_pk_mul_f32 v[146:147], v[122:123], v[144:145] op_sel_hi:[1,0]
	v_pk_mul_f32 v[152:153], v[124:125], v[144:145] op_sel_hi:[1,0]
	v_pk_mul_f32 v[148:149], v[110:111], v[144:145] op_sel_hi:[1,0]
	v_pk_mul_f32 v[150:151], v[112:113], v[144:145] op_sel_hi:[1,0]
	s_cbranch_scc1 .LBB0_1160
	v_mul_f32_e32 v146, 0xbfb8aa3b, v146
	v_mul_f32_e32 v147, 0xbfb8aa3b, v147
	v_mul_f32_e32 v152, 0xbfb8aa3b, v152
	v_mul_f32_e32 v153, 0xbfb8aa3b, v153
	v_mul_f32_e32 v148, 0xbfb8aa3b, v148
	v_mul_f32_e32 v149, 0xbfb8aa3b, v149
	v_mul_f32_e32 v150, 0xbfb8aa3b, v150
	v_mul_f32_e32 v151, 0xbfb8aa3b, v151
	v_exp_f32_e32 v146, v146
	v_exp_f32_e32 v147, v147
	v_exp_f32_e32 v152, v152
	v_exp_f32_e32 v153, v153
	v_exp_f32_e32 v148, v148
	v_exp_f32_e32 v149, v149
	v_exp_f32_e32 v150, v150
	v_exp_f32_e32 v151, v151
	v_add_f32_e32 v146, 1.0, v146
	v_add_f32_e32 v147, 1.0, v147
	v_add_f32_e32 v152, 1.0, v152
	v_add_f32_e32 v153, 1.0, v153
	v_add_f32_e32 v148, 1.0, v148
	v_add_f32_e32 v149, 1.0, v149
	v_add_f32_e32 v150, 1.0, v150
	v_add_f32_e32 v151, 1.0, v151
	v_rcp_f32_e32 v146, v146
	v_rcp_f32_e32 v147, v147
	v_rcp_f32_e32 v152, v152
	v_rcp_f32_e32 v153, v153
	v_rcp_f32_e32 v148, v148
	v_rcp_f32_e32 v149, v149
	v_rcp_f32_e32 v150, v150
	v_rcp_f32_e32 v151, v151
